# same gate-ratio running-sum epilogue applied to the sample-row up-projection units in P3 (16 CUs on that phase's critical path)
# baseline (speedup 1.0000x reference)
; #define PG8_STAGE(bufoff, gbase, voff) do { _Pragma("unroll") for (int _i = 0; _i < 2; ++_i) \
;         __builtin_amdgcn_global_load_lds((const unsigned*)((const char*)(gbase) + (voff)[_i]), (LAS unsigned*)(lds + (bufoff) + ldsw + _i * 8192), 16, 0, 0); } while (0)
; #define PG8_LDA(dst, b, h) do { _Pragma("unroll") for (int m = 0; m < 4; ++m) _Pragma("unroll") for (int k = 0; k < 2; ++k) dst[m][k] = *(const LAS bf16x8*)(lds + PG8_SA(b, h) + aoff + m * 2048 + k * 1024); } while (0)
; #define PG8_LDB(dst, b, h) do { _Pragma("unroll") for (int n = 0; n < 2; ++n) _Pragma("unroll") for (int k = 0; k < 2; ++k) dst[n][k] = *(const LAS bf16x8*)(lds + PG8_SB(b, h) + boff + n * 2048 + k * 1024); } while (0)
; #define PG8_MMA(ai, bj, At, Bt) do { __builtin_amdgcn_s_setprio(1); _Pragma("unroll") for (int m = 0; m < 4; ++m) _Pragma("unroll") for (int n = 0; n < 2; ++n) _Pragma("unroll") for (int k = 0; k < 2; ++k) \
;         acc[ai][bj][m][n] = __builtin_amdgcn_mfma_f32_16x16x32_bf16(Bt[n][k], At[m][k], acc[ai][bj][m][n], 0, 0, 0); __builtin_amdgcn_s_setprio(0); } while (0)
; #define PG8_WAIT_V(n) asm volatile("s_waitcnt vmcnt(" #n ")" ::: "memory")
; template <class Epi, class Sched>
; DI void gemm_phase(LAS unsigned char* lds, const Sched& S, const Epi& E) {
;     ...
;         const bool has_next = S.next(ui + 1, nxt);
;         const char* nA = has_next ? S.pa(nxt) : cA; const char* nB = has_next ? S.pb(nxt) : cB;
;         for (int t = 0; t < nt; t += 2) {
;             const bool last = (t == nt - 2);
;             const char* a1 = cA + (size_t)(t + 1) * kstep;
;             const char* a2 = last ? nA : cA + (size_t)(t + 2) * kstep; const char* b2 = last ? nB : cB + (size_t)(t + 2) * kstep;
;             const char* a3 = a2 + kstep; const char* b3 = b2 + kstep;
;             PG8_LDB(B0, 0, 0); PG8_LDB(B1, 0, 1); PG8_SCHED; PG8_LDA(At, 0, 0); PG8_STAGE(PG8_SA(1, 1), a1 + hstepA, voffA);
;             PG8_WAIT_V(8); PG8_WAIT_L(0); PG8_BAR; PG8_MMA(0, 0, At, B0); PG8_MMA(0, 1, At, B1); PG8_BAR; PG8_SCHED;
;     ...
; #pragma unroll
;         for (int a = 0; a < 2; ++a)
; #pragma unroll
;             for (int b = 0; b < 2; ++b)
; #pragma unroll
;                 for (int m = 0; m < 4; ++m)
; #pragma unroll
;                     for (int n = 0; n < 2; ++n) acc[a][b][m][n] = (f32x4){0.f, 0.f, 0.f, 0.f};
;         cur = nxt; cA = nA; cB = nB; ++ui;
.LBB0_944:
	s_mov_b32 s8, s82
	s_mov_b32 s84, s82
	s_add_i32 s82, s82, 1
	s_cmp_lt_u32 s84, 2
	s_cselect_b64 s[24:25], -1, 0
	s_mov_b64 s[26:27], s[6:7]
	s_and_b64 s[6:7], s[24:25], exec
	s_cselect_b32 s8, s82, s8
	s_cmp_lg_u32 s84, 0
	s_cselect_b64 s[22:23], -1, 0
	s_cmp_eq_u32 s84, 0
	s_cselect_b32 s6, s40, 0x1600
	s_add_u32 s17, s4, s6
	s_addc_u32 s85, s5, 0
	s_and_b64 s[6:7], s[24:25], exec
	s_mov_b64 s[28:29], s[20:21]
	s_cselect_b32 s21, s85, s29
	s_cselect_b32 s20, s17, s28
	s_lshl_b32 s6, s8, 10
	s_or_b32 s6, s6, s30
	s_ashr_i32 s7, s6, 31
	s_lshl_b64 s[6:7], s[6:7], 10
	s_add_u32 s6, s3, s6
	s_addc_u32 s7, s45, s7
	s_and_b64 s[24:25], s[24:25], exec
	s_cselect_b32 s8, s7, s27
	s_cselect_b32 s17, s6, s26
	s_add_u32 s24, s28, 0x190080
	s_addc_u32 s25, s29, 0
	s_add_u32 s85, s26, 0x100
	s_addc_u32 s86, s27, 0
	s_mov_b32 s87, -2
	s_cmp_lg_u32 s84, 0
	s_cbranch_scc1 .Lup3_nozero
	v_mov_b32_e32 v2, 0
	v_mov_b32_e32 v3, v2
	v_mov_b32_e32 v4, v2
	v_mov_b32_e32 v5, v2
	v_mov_b32_e32 v6, v2
	v_mov_b32_e32 v7, v2
	v_mov_b32_e32 v8, v2
	v_mov_b32_e32 v9, v2
	v_mov_b32_e32 v10, v2
	v_mov_b32_e32 v11, v2
	v_mov_b32_e32 v12, v2
	v_mov_b32_e32 v13, v2
	v_mov_b32_e32 v18, v2
	v_mov_b32_e32 v19, v2
	v_mov_b32_e32 v20, v2
	v_mov_b32_e32 v21, v2
	v_mov_b32_e32 v26, v2
	v_mov_b32_e32 v27, v2
	v_mov_b32_e32 v28, v2
	v_mov_b32_e32 v29, v2
	v_mov_b32_e32 v34, v2
	v_mov_b32_e32 v35, v2
	v_mov_b32_e32 v36, v2
	v_mov_b32_e32 v37, v2
	v_mov_b32_e32 v42, v2
	v_mov_b32_e32 v43, v2
	v_mov_b32_e32 v44, v2
	v_mov_b32_e32 v45, v2
	v_mov_b32_e32 v50, v2
	v_mov_b32_e32 v51, v2
	v_mov_b32_e32 v52, v2
	v_mov_b32_e32 v53, v2
	v_mov_b32_e32 v14, v2
	v_mov_b32_e32 v15, v2
	v_mov_b32_e32 v16, v2
	v_mov_b32_e32 v17, v2
	v_mov_b32_e32 v22, v2
	v_mov_b32_e32 v23, v2
	v_mov_b32_e32 v24, v2
	v_mov_b32_e32 v25, v2
	v_mov_b32_e32 v30, v2
	v_mov_b32_e32 v31, v2
	v_mov_b32_e32 v32, v2
	v_mov_b32_e32 v33, v2
	v_mov_b32_e32 v38, v2
	v_mov_b32_e32 v39, v2
	v_mov_b32_e32 v40, v2
	v_mov_b32_e32 v41, v2
	v_mov_b32_e32 v46, v2
	v_mov_b32_e32 v47, v2
	v_mov_b32_e32 v48, v2
	v_mov_b32_e32 v49, v2
	v_mov_b32_e32 v54, v2
	v_mov_b32_e32 v55, v2
	v_mov_b32_e32 v56, v2
	v_mov_b32_e32 v57, v2
	v_mov_b32_e32 v58, v2
	v_mov_b32_e32 v59, v2
	v_mov_b32_e32 v60, v2
	v_mov_b32_e32 v61, v2
	v_mov_b32_e32 v62, v2
	v_mov_b32_e32 v63, v2
	v_mov_b32_e32 v64, v2
	v_mov_b32_e32 v65, v2
	v_mov_b32_e32 v66, v2
	v_mov_b32_e32 v67, v2
	v_mov_b32_e32 v68, v2
	v_mov_b32_e32 v69, v2
	v_mov_b32_e32 v70, v2
	v_mov_b32_e32 v71, v2
	v_mov_b32_e32 v72, v2
	v_mov_b32_e32 v73, v2
	v_mov_b32_e32 v74, v2
	v_mov_b32_e32 v75, v2
	v_mov_b32_e32 v76, v2
	v_mov_b32_e32 v77, v2
	v_mov_b32_e32 v82, v2
	v_mov_b32_e32 v83, v2
	v_mov_b32_e32 v84, v2
	v_mov_b32_e32 v85, v2
	v_mov_b32_e32 v90, v2
	v_mov_b32_e32 v91, v2
	v_mov_b32_e32 v92, v2
	v_mov_b32_e32 v93, v2
	v_mov_b32_e32 v98, v2
	v_mov_b32_e32 v99, v2
	v_mov_b32_e32 v100, v2
	v_mov_b32_e32 v101, v2
	v_mov_b32_e32 v110, v2
	v_mov_b32_e32 v111, v2
	v_mov_b32_e32 v112, v2
	v_mov_b32_e32 v113, v2
	v_mov_b32_e32 v114, v2
	v_mov_b32_e32 v115, v2
	v_mov_b32_e32 v116, v2
	v_mov_b32_e32 v117, v2
	v_mov_b32_e32 v78, v2
	v_mov_b32_e32 v79, v2
	v_mov_b32_e32 v80, v2
	v_mov_b32_e32 v81, v2
	v_mov_b32_e32 v86, v2
	v_mov_b32_e32 v87, v2
	v_mov_b32_e32 v88, v2
	v_mov_b32_e32 v89, v2
	v_mov_b32_e32 v94, v2
	v_mov_b32_e32 v95, v2
	v_mov_b32_e32 v96, v2
	v_mov_b32_e32 v97, v2
	v_mov_b32_e32 v102, v2
	v_mov_b32_e32 v103, v2
	v_mov_b32_e32 v104, v2
	v_mov_b32_e32 v105, v2
	v_mov_b32_e32 v106, v2
	v_mov_b32_e32 v107, v2
	v_mov_b32_e32 v108, v2
	v_mov_b32_e32 v109, v2
	v_mov_b32_e32 v118, v2
	v_mov_b32_e32 v119, v2
	v_mov_b32_e32 v120, v2
	v_mov_b32_e32 v121, v2
	v_mov_b32_e32 v122, v2
	v_mov_b32_e32 v123, v2
	v_mov_b32_e32 v124, v2
	v_mov_b32_e32 v125, v2
	v_mov_b32_e32 v126, v2
	v_mov_b32_e32 v127, v2
	v_mov_b32_e32 v128, v2
	v_mov_b32_e32 v129, v2
.Lup3_nozero:
	s_waitcnt vmcnt(0)
.LBB0_945:
	ds_read_b128 v[130:133], v173
	ds_read_b128 v[134:137], v173 offset:1024
	ds_read_b128 v[138:141], v173 offset:2048
	ds_read_b128 v[142:145], v173 offset:3072
	ds_read_b128 v[146:149], v174
	ds_read_b128 v[150:153], v174 offset:1024
	ds_read_b128 v[166:169], v174 offset:2048
	ds_read_b128 v[178:181], v174 offset:3072
	s_add_u32 s26, s24, 0xffe70080
	s_addc_u32 s27, s25, -1
	s_cmp_eq_u32 s87, 4
	s_cselect_b32 s29, s21, s27
	s_cselect_b32 s28, s20, s26
	s_cselect_b32 s27, s8, s86
	s_cselect_b32 s26, s17, s85
	s_mov_b32 m0, s74
	v_lshl_add_u64 v[216:217], s[24:25], 0, v[162:163]
	ds_read_b128 v[184:187], v175
	ds_read_b128 v[188:191], v175 offset:1024
	ds_read_b128 v[192:195], v175 offset:2048
	ds_read_b128 v[196:199], v175 offset:3072
	ds_read_b128 v[200:203], v175 offset:4096
	ds_read_b128 v[204:207], v175 offset:5120
	ds_read_b128 v[208:211], v175 offset:6144
	ds_read_b128 v[212:215], v175 offset:7168
	global_load_lds_dwordx4 v[216:217], off
	v_lshl_add_u64 v[216:217], s[24:25], 0, v[164:165]
	s_mov_b32 m0, s75
	s_nop 0
	global_load_lds_dwordx4 v[216:217], off
	s_waitcnt vmcnt(8)
	s_waitcnt lgkmcnt(0)
	s_barrier
; #define PG8_STAGE(bufoff, gbase, voff) do { _Pragma("unroll") for (int _i = 0; _i < 2; ++_i) \
;         __builtin_amdgcn_global_load_lds((const unsigned*)((const char*)(gbase) + (voff)[_i]), (LAS unsigned*)(lds + (bufoff) + ldsw + _i * 8192), 16, 0, 0); } while (0)
; #define PG8_LDA(dst, b, h) do { _Pragma("unroll") for (int m = 0; m < 4; ++m) _Pragma("unroll") for (int k = 0; k < 2; ++k) dst[m][k] = *(const LAS bf16x8*)(lds + PG8_SA(b, h) + aoff + m * 2048 + k * 1024); } while (0)
; #define PG8_MMA(ai, bj, At, Bt) do { __builtin_amdgcn_s_setprio(1); _Pragma("unroll") for (int m = 0; m < 4; ++m) _Pragma("unroll") for (int n = 0; n < 2; ++n) _Pragma("unroll") for (int k = 0; k < 2; ++k) \
;         acc[ai][bj][m][n] = __builtin_amdgcn_mfma_f32_16x16x32_bf16(Bt[n][k], At[m][k], acc[ai][bj][m][n], 0, 0, 0); __builtin_amdgcn_s_setprio(0); } while (0)
; #define PG8_WAIT_V(n) asm volatile("s_waitcnt vmcnt(" #n ")" ::: "memory")
; #define PG8_WAIT_L(n) asm volatile("s_waitcnt lgkmcnt(" #n ")" ::: "memory")
; #define PG8_BAR __builtin_amdgcn_s_barrier()
; #define PG8_SCHED __builtin_amdgcn_sched_barrier(0)
; template <class Epi, class Sched>
; DI void gemm_phase(LAS unsigned char* lds, const Sched& S, const Epi& E) {
;     ...
;             PG8_WAIT_V(8); PG8_WAIT_L(0); PG8_BAR; PG8_MMA(0, 0, At, B0); PG8_MMA(0, 1, At, B1); PG8_BAR; PG8_SCHED;
;             PG8_LDA(At, 0, 1); PG8_STAGE(PG8_SB(0, 0), b2, voffB); PG8_STAGE(PG8_SB(0, 1), b2 + hstepB, voffB); PG8_STAGE(PG8_SA(0, 0), a2, voffA);
;             PG8_WAIT_V(8); PG8_WAIT_L(0); PG8_BAR; PG8_MMA(1, 0, At, B0); PG8_MMA(1, 1, At, B1); PG8_BAR; PG8_SCHED;
	s_setprio 1
	s_waitcnt lgkmcnt(0)
	v_mfma_f32_16x16x32_bf16 v[126:129], v[130:133], v[184:187], v[126:129]
	v_mfma_f32_16x16x32_bf16 v[122:125], v[138:141], v[184:187], v[122:125]
	v_mfma_f32_16x16x32_bf16 v[118:121], v[130:133], v[192:195], v[118:121]
	v_mfma_f32_16x16x32_bf16 v[106:109], v[138:141], v[192:195], v[106:109]
	v_mfma_f32_16x16x32_bf16 v[102:105], v[130:133], v[200:203], v[102:105]
	v_mfma_f32_16x16x32_bf16 v[94:97], v[138:141], v[200:203], v[94:97]
	v_mfma_f32_16x16x32_bf16 v[86:89], v[130:133], v[208:211], v[86:89]
	v_mfma_f32_16x16x32_bf16 v[78:81], v[138:141], v[208:211], v[78:81]
	v_mfma_f32_16x16x32_bf16 v[126:129], v[134:137], v[188:191], v[126:129]
	v_mfma_f32_16x16x32_bf16 v[122:125], v[142:145], v[188:191], v[122:125]
	v_mfma_f32_16x16x32_bf16 v[118:121], v[134:137], v[196:199], v[118:121]
	v_mfma_f32_16x16x32_bf16 v[106:109], v[142:145], v[196:199], v[106:109]
	v_mfma_f32_16x16x32_bf16 v[102:105], v[134:137], v[204:207], v[102:105]
	v_mfma_f32_16x16x32_bf16 v[94:97], v[142:145], v[204:207], v[94:97]
	v_mfma_f32_16x16x32_bf16 v[86:89], v[134:137], v[212:215], v[86:89]
	v_mfma_f32_16x16x32_bf16 v[78:81], v[142:145], v[212:215], v[78:81]
	s_setprio 0
	s_setprio 1
	v_mfma_f32_16x16x32_bf16 v[114:117], v[146:149], v[184:187], v[114:117]
	v_mfma_f32_16x16x32_bf16 v[110:113], v[166:169], v[184:187], v[110:113]
	v_mfma_f32_16x16x32_bf16 v[98:101], v[146:149], v[192:195], v[98:101]
	v_mfma_f32_16x16x32_bf16 v[90:93], v[166:169], v[192:195], v[90:93]
	v_mfma_f32_16x16x32_bf16 v[82:85], v[146:149], v[200:203], v[82:85]
	v_mfma_f32_16x16x32_bf16 v[74:77], v[166:169], v[200:203], v[74:77]
	v_mfma_f32_16x16x32_bf16 v[70:73], v[146:149], v[208:211], v[70:73]
	v_mfma_f32_16x16x32_bf16 v[66:69], v[166:169], v[208:211], v[66:69]
	v_mfma_f32_16x16x32_bf16 v[114:117], v[150:153], v[188:191], v[114:117]
	v_mfma_f32_16x16x32_bf16 v[110:113], v[178:181], v[188:191], v[110:113]
	v_mfma_f32_16x16x32_bf16 v[98:101], v[150:153], v[196:199], v[98:101]
	v_mfma_f32_16x16x32_bf16 v[90:93], v[178:181], v[196:199], v[90:93]
	v_mfma_f32_16x16x32_bf16 v[82:85], v[150:153], v[204:207], v[82:85]
	v_mfma_f32_16x16x32_bf16 v[74:77], v[178:181], v[204:207], v[74:77]
	v_mfma_f32_16x16x32_bf16 v[70:73], v[150:153], v[212:215], v[70:73]
	v_mfma_f32_16x16x32_bf16 v[66:69], v[178:181], v[212:215], v[66:69]
	s_setprio 0
	s_barrier
	s_mov_b32 m0, s76
	v_lshl_add_u64 v[216:217], s[26:27], 0, v[156:157]
	s_add_u32 s88, s26, 0x20000
	ds_read_b128 v[184:187], v175 offset:16384
	ds_read_b128 v[188:191], v175 offset:17408
	ds_read_b128 v[192:195], v175 offset:18432
	ds_read_b128 v[196:199], v175 offset:19456
	ds_read_b128 v[200:203], v175 offset:20480
	ds_read_b128 v[204:207], v175 offset:21504
	ds_read_b128 v[208:211], v175 offset:22528
	ds_read_b128 v[212:215], v175 offset:23552
	global_load_lds_dwordx4 v[216:217], off
	v_lshl_add_u64 v[218:219], s[26:27], 0, v[160:161]
	s_mov_b32 m0, s77
	s_addc_u32 s89, s27, 0
	global_load_lds_dwordx4 v[218:219], off
	v_lshl_add_u64 v[220:221], s[88:89], 0, v[156:157]
	s_mov_b32 m0, s78
	v_lshl_add_u64 v[222:223], s[28:29], 0, v[158:159]
	global_load_lds_dwordx4 v[220:221], off
	v_lshl_add_u64 v[220:221], s[88:89], 0, v[160:161]
	s_mov_b32 m0, s79
	s_nop 0
	global_load_lds_dwordx4 v[220:221], off
	v_lshl_add_u64 v[220:221], s[28:29], 0, v[154:155]
	s_mov_b32 m0, s33
	s_nop 0
	global_load_lds_dwordx4 v[220:221], off
	s_mov_b32 m0, s34
	s_nop 0
	global_load_lds_dwordx4 v[222:223], off
	s_waitcnt vmcnt(8)
	s_waitcnt lgkmcnt(0)
	s_barrier
	s_setprio 1
	s_waitcnt lgkmcnt(0)
	v_mfma_f32_16x16x32_bf16 v[62:65], v[130:133], v[184:187], v[62:65]
	v_mfma_f32_16x16x32_bf16 v[58:61], v[138:141], v[184:187], v[58:61]
	v_mfma_f32_16x16x32_bf16 v[54:57], v[130:133], v[192:195], v[54:57]
	v_mfma_f32_16x16x32_bf16 v[46:49], v[138:141], v[192:195], v[46:49]
	v_mfma_f32_16x16x32_bf16 v[38:41], v[130:133], v[200:203], v[38:41]
	v_mfma_f32_16x16x32_bf16 v[30:33], v[138:141], v[200:203], v[30:33]
	v_mfma_f32_16x16x32_bf16 v[22:25], v[130:133], v[208:211], v[22:25]
	v_mfma_f32_16x16x32_bf16 v[14:17], v[138:141], v[208:211], v[14:17]
	v_mfma_f32_16x16x32_bf16 v[62:65], v[134:137], v[188:191], v[62:65]
	v_mfma_f32_16x16x32_bf16 v[58:61], v[142:145], v[188:191], v[58:61]
	v_mfma_f32_16x16x32_bf16 v[54:57], v[134:137], v[196:199], v[54:57]
	v_mfma_f32_16x16x32_bf16 v[46:49], v[142:145], v[196:199], v[46:49]
	v_mfma_f32_16x16x32_bf16 v[38:41], v[134:137], v[204:207], v[38:41]
	v_mfma_f32_16x16x32_bf16 v[30:33], v[142:145], v[204:207], v[30:33]
	v_mfma_f32_16x16x32_bf16 v[22:25], v[134:137], v[212:215], v[22:25]
	v_mfma_f32_16x16x32_bf16 v[14:17], v[142:145], v[212:215], v[14:17]
	s_setprio 0
	s_setprio 1
	v_mfma_f32_16x16x32_bf16 v[50:53], v[146:149], v[184:187], v[50:53]
	v_mfma_f32_16x16x32_bf16 v[42:45], v[166:169], v[184:187], v[42:45]
	v_mfma_f32_16x16x32_bf16 v[34:37], v[146:149], v[192:195], v[34:37]
	v_mfma_f32_16x16x32_bf16 v[26:29], v[166:169], v[192:195], v[26:29]
	v_mfma_f32_16x16x32_bf16 v[18:21], v[146:149], v[200:203], v[18:21]
	v_mfma_f32_16x16x32_bf16 v[10:13], v[166:169], v[200:203], v[10:13]
	v_mfma_f32_16x16x32_bf16 v[6:9], v[146:149], v[208:211], v[6:9]
	v_mfma_f32_16x16x32_bf16 v[2:5], v[166:169], v[208:211], v[2:5]
	v_mfma_f32_16x16x32_bf16 v[50:53], v[150:153], v[188:191], v[50:53]
	v_mfma_f32_16x16x32_bf16 v[42:45], v[178:181], v[188:191], v[42:45]
	v_mfma_f32_16x16x32_bf16 v[34:37], v[150:153], v[196:199], v[34:37]
	v_mfma_f32_16x16x32_bf16 v[26:29], v[178:181], v[196:199], v[26:29]
	v_mfma_f32_16x16x32_bf16 v[18:21], v[150:153], v[204:207], v[18:21]
	v_mfma_f32_16x16x32_bf16 v[10:13], v[178:181], v[204:207], v[10:13]
	v_mfma_f32_16x16x32_bf16 v[6:9], v[150:153], v[212:215], v[6:9]
	v_mfma_f32_16x16x32_bf16 v[2:5], v[178:181], v[212:215], v[2:5]
	s_setprio 0
	s_barrier
; #define PG8_STAGE(bufoff, gbase, voff) do { _Pragma("unroll") for (int _i = 0; _i < 2; ++_i) \
;         __builtin_amdgcn_global_load_lds((const unsigned*)((const char*)(gbase) + (voff)[_i]), (LAS unsigned*)(lds + (bufoff) + ldsw + _i * 8192), 16, 0, 0); } while (0)
; #define PG8_LDA(dst, b, h) do { _Pragma("unroll") for (int m = 0; m < 4; ++m) _Pragma("unroll") for (int k = 0; k < 2; ++k) dst[m][k] = *(const LAS bf16x8*)(lds + PG8_SA(b, h) + aoff + m * 2048 + k * 1024); } while (0)
; #define PG8_LDB(dst, b, h) do { _Pragma("unroll") for (int n = 0; n < 2; ++n) _Pragma("unroll") for (int k = 0; k < 2; ++k) dst[n][k] = *(const LAS bf16x8*)(lds + PG8_SB(b, h) + boff + n * 2048 + k * 1024); } while (0)
; #define PG8_MMA(ai, bj, At, Bt) do { __builtin_amdgcn_s_setprio(1); _Pragma("unroll") for (int m = 0; m < 4; ++m) _Pragma("unroll") for (int n = 0; n < 2; ++n) _Pragma("unroll") for (int k = 0; k < 2; ++k) \
;         acc[ai][bj][m][n] = __builtin_amdgcn_mfma_f32_16x16x32_bf16(Bt[n][k], At[m][k], acc[ai][bj][m][n], 0, 0, 0); __builtin_amdgcn_s_setprio(0); } while (0)
; #define PG8_WAIT_V(n) asm volatile("s_waitcnt vmcnt(" #n ")" ::: "memory")
; #define PG8_WAIT_L(n) asm volatile("s_waitcnt lgkmcnt(" #n ")" ::: "memory")
; #define PG8_BAR __builtin_amdgcn_s_barrier()
; #define PG8_SCHED __builtin_amdgcn_sched_barrier(0)
; template <class Epi, class Sched>
; DI void gemm_phase(LAS unsigned char* lds, const Sched& S, const Epi& E) {
;     ...
;             PG8_LDB(B0, 1, 0); PG8_LDB(B1, 1, 1); PG8_SCHED; PG8_LDA(At, 1, 0); PG8_STAGE(PG8_SA(0, 1), a2 + hstepA, voffA);
;             PG8_WAIT_V(8); PG8_WAIT_L(0); PG8_BAR; PG8_MMA(0, 0, At, B0); PG8_MMA(0, 1, At, B1); PG8_BAR; PG8_SCHED;
;             PG8_LDA(At, 1, 1); PG8_STAGE(PG8_SB(1, 0), b3, voffB); PG8_STAGE(PG8_SB(1, 1), b3 + hstepB, voffB); PG8_STAGE(PG8_SA(1, 0), a3, voffA);
	ds_read_b128 v[130:133], v176
	ds_read_b128 v[134:137], v176 offset:1024
	ds_read_b128 v[138:141], v176 offset:2048
	ds_read_b128 v[142:145], v176 offset:3072
	ds_read_b128 v[146:149], v177
	ds_read_b128 v[150:153], v177 offset:1024
	ds_read_b128 v[166:169], v177 offset:2048
	ds_read_b128 v[178:181], v177 offset:3072
	s_add_u32 s28, s28, 0x190000
	s_addc_u32 s29, s29, 0
	s_mov_b32 m0, s35
	v_lshl_add_u64 v[224:225], s[28:29], 0, v[154:155]
	ds_read_b128 v[184:187], v175 offset:32768
	ds_read_b128 v[188:191], v175 offset:33792
	ds_read_b128 v[192:195], v175 offset:34816
	ds_read_b128 v[196:199], v175 offset:35840
	ds_read_b128 v[200:203], v175 offset:36864
	ds_read_b128 v[204:207], v175 offset:37888
	ds_read_b128 v[208:211], v175 offset:38912
	ds_read_b128 v[212:215], v175 offset:39936
	global_load_lds_dwordx4 v[224:225], off
	v_lshl_add_u64 v[224:225], s[28:29], 0, v[158:159]
	s_mov_b32 m0, s36
	s_nop 0
	global_load_lds_dwordx4 v[224:225], off
	s_waitcnt vmcnt(8)
	s_waitcnt lgkmcnt(0)
	s_barrier
	s_setprio 1
	s_waitcnt lgkmcnt(0)
	v_mfma_f32_16x16x32_bf16 v[126:129], v[130:133], v[184:187], v[126:129]
	v_mfma_f32_16x16x32_bf16 v[122:125], v[138:141], v[184:187], v[122:125]
	v_mfma_f32_16x16x32_bf16 v[118:121], v[130:133], v[192:195], v[118:121]
	v_mfma_f32_16x16x32_bf16 v[106:109], v[138:141], v[192:195], v[106:109]
	v_mfma_f32_16x16x32_bf16 v[102:105], v[130:133], v[200:203], v[102:105]
	v_mfma_f32_16x16x32_bf16 v[94:97], v[138:141], v[200:203], v[94:97]
	v_mfma_f32_16x16x32_bf16 v[86:89], v[130:133], v[208:211], v[86:89]
	v_mfma_f32_16x16x32_bf16 v[78:81], v[138:141], v[208:211], v[78:81]
	v_mfma_f32_16x16x32_bf16 v[126:129], v[134:137], v[188:191], v[126:129]
	v_mfma_f32_16x16x32_bf16 v[122:125], v[142:145], v[188:191], v[122:125]
	v_mfma_f32_16x16x32_bf16 v[118:121], v[134:137], v[196:199], v[118:121]
	v_mfma_f32_16x16x32_bf16 v[106:109], v[142:145], v[196:199], v[106:109]
	v_mfma_f32_16x16x32_bf16 v[102:105], v[134:137], v[204:207], v[102:105]
	v_mfma_f32_16x16x32_bf16 v[94:97], v[142:145], v[204:207], v[94:97]
	v_mfma_f32_16x16x32_bf16 v[86:89], v[134:137], v[212:215], v[86:89]
	v_mfma_f32_16x16x32_bf16 v[78:81], v[142:145], v[212:215], v[78:81]
	s_setprio 0
	s_setprio 1
	v_mfma_f32_16x16x32_bf16 v[114:117], v[146:149], v[184:187], v[114:117]
	v_mfma_f32_16x16x32_bf16 v[110:113], v[166:169], v[184:187], v[110:113]
	v_mfma_f32_16x16x32_bf16 v[98:101], v[146:149], v[192:195], v[98:101]
	v_mfma_f32_16x16x32_bf16 v[90:93], v[166:169], v[192:195], v[90:93]
	v_mfma_f32_16x16x32_bf16 v[82:85], v[146:149], v[200:203], v[82:85]
	v_mfma_f32_16x16x32_bf16 v[74:77], v[166:169], v[200:203], v[74:77]
	v_mfma_f32_16x16x32_bf16 v[70:73], v[146:149], v[208:211], v[70:73]
	v_mfma_f32_16x16x32_bf16 v[66:69], v[166:169], v[208:211], v[66:69]
	v_mfma_f32_16x16x32_bf16 v[114:117], v[150:153], v[188:191], v[114:117]
	v_mfma_f32_16x16x32_bf16 v[110:113], v[178:181], v[188:191], v[110:113]
	v_mfma_f32_16x16x32_bf16 v[98:101], v[150:153], v[196:199], v[98:101]
	v_mfma_f32_16x16x32_bf16 v[90:93], v[178:181], v[196:199], v[90:93]
	v_mfma_f32_16x16x32_bf16 v[82:85], v[150:153], v[204:207], v[82:85]
	v_mfma_f32_16x16x32_bf16 v[74:77], v[178:181], v[204:207], v[74:77]
	v_mfma_f32_16x16x32_bf16 v[70:73], v[150:153], v[212:215], v[70:73]
	v_mfma_f32_16x16x32_bf16 v[66:69], v[178:181], v[212:215], v[66:69]
	s_setprio 0
	s_barrier
	s_mov_b32 m0, s81
	v_lshl_add_u64 v[216:217], v[216:217], 0, s[12:13]
	ds_read_b128 v[184:187], v175 offset:49152
	ds_read_b128 v[188:191], v175 offset:50176
	ds_read_b128 v[192:195], v175 offset:51200
	ds_read_b128 v[196:199], v175 offset:52224
	ds_read_b128 v[200:203], v175 offset:53248
	ds_read_b128 v[204:207], v175 offset:54272
	ds_read_b128 v[208:211], v175 offset:55296
	ds_read_b128 v[212:215], v175 offset:56320
	global_load_lds_dwordx4 v[216:217], off
	s_add_i32 m0, s81, 0x2000
	s_add_u32 s26, s26, 0x20080
	v_lshl_add_u64 v[216:217], v[218:219], 0, s[12:13]
	s_addc_u32 s27, s27, 0
	s_add_i32 s28, s80, s31
	global_load_lds_dwordx4 v[216:217], off
	v_lshl_add_u64 v[216:217], s[26:27], 0, v[156:157]
	s_mov_b32 m0, s28
	s_nop 0
	global_load_lds_dwordx4 v[216:217], off
	v_lshl_add_u64 v[216:217], s[26:27], 0, v[160:161]
	s_add_i32 m0, s28, 0x2000
	s_nop 0
	global_load_lds_dwordx4 v[216:217], off
	v_lshl_add_u64 v[216:217], v[220:221], 0, s[12:13]
	s_mov_b32 m0, s37
	s_nop 0
	global_load_lds_dwordx4 v[216:217], off
	v_lshl_add_u64 v[216:217], v[222:223], 0, s[12:13]
	s_mov_b32 m0, s38
	s_nop 0
	global_load_lds_dwordx4 v[216:217], off
	s_waitcnt vmcnt(8)
	s_waitcnt lgkmcnt(0)
	s_barrier
; #define PG8_MMA(ai, bj, At, Bt) do { __builtin_amdgcn_s_setprio(1); _Pragma("unroll") for (int m = 0; m < 4; ++m) _Pragma("unroll") for (int n = 0; n < 2; ++n) _Pragma("unroll") for (int k = 0; k < 2; ++k) \
;         acc[ai][bj][m][n] = __builtin_amdgcn_mfma_f32_16x16x32_bf16(Bt[n][k], At[m][k], acc[ai][bj][m][n], 0, 0, 0); __builtin_amdgcn_s_setprio(0); } while (0)
; #define PG8_WAIT_V(n) asm volatile("s_waitcnt vmcnt(" #n ")" ::: "memory")
; #define PG8_WAIT_L(n) asm volatile("s_waitcnt lgkmcnt(" #n ")" ::: "memory")
; #define PG8_BAR __builtin_amdgcn_s_barrier()
; #define PG8_SCHED __builtin_amdgcn_sched_barrier(0)
; template <class Epi, class Sched>
; DI void gemm_phase(LAS unsigned char* lds, const Sched& S, const Epi& E) {
;     ...
;             PG8_WAIT_V(8); PG8_WAIT_L(0); PG8_BAR; PG8_MMA(1, 0, At, B0); PG8_MMA(1, 1, At, B1); PG8_BAR; PG8_SCHED;
;         }
;         if (wr == 0) PG8_BAR;
;         E(acc, cur, wr, wc, fr, fq);
;     DI void operator()(Acc& acc, const Unit& u, int wr, int wc, int fr, int fq) const {
;     ...
;         bf16_t* base = proj + (size_t)(u.pm * 256 + wr * 64 + fr) * NPJ + C_GL + u.pn * 256 + wc * 32 + fq * 8;
;         {
;             u32x4 g[2][4][2];
; #pragma unroll
;             for (int ai = 0; ai < 2; ++ai)
; #pragma unroll
;                 for (int m = 0; m < 4; ++m)
; #pragma unroll
;                     for (int bj = 0; bj < 2; ++bj) g[ai][m][bj] = *(const u32x4*)(base + (size_t)(ai * 128 + m * 16) * NPJ + u.k * 1024 + bj * 128);
	s_setprio 1
	s_waitcnt lgkmcnt(0)
	v_mfma_f32_16x16x32_bf16 v[62:65], v[130:133], v[184:187], v[62:65]
	v_mfma_f32_16x16x32_bf16 v[58:61], v[138:141], v[184:187], v[58:61]
	v_mfma_f32_16x16x32_bf16 v[54:57], v[130:133], v[192:195], v[54:57]
	v_mfma_f32_16x16x32_bf16 v[46:49], v[138:141], v[192:195], v[46:49]
	v_mfma_f32_16x16x32_bf16 v[38:41], v[130:133], v[200:203], v[38:41]
	v_mfma_f32_16x16x32_bf16 v[30:33], v[138:141], v[200:203], v[30:33]
	v_mfma_f32_16x16x32_bf16 v[22:25], v[130:133], v[208:211], v[22:25]
	v_mfma_f32_16x16x32_bf16 v[14:17], v[138:141], v[208:211], v[14:17]
	v_mfma_f32_16x16x32_bf16 v[62:65], v[134:137], v[188:191], v[62:65]
	v_mfma_f32_16x16x32_bf16 v[58:61], v[142:145], v[188:191], v[58:61]
	v_mfma_f32_16x16x32_bf16 v[54:57], v[134:137], v[196:199], v[54:57]
	v_mfma_f32_16x16x32_bf16 v[46:49], v[142:145], v[196:199], v[46:49]
	v_mfma_f32_16x16x32_bf16 v[38:41], v[134:137], v[204:207], v[38:41]
	v_mfma_f32_16x16x32_bf16 v[30:33], v[142:145], v[204:207], v[30:33]
	v_mfma_f32_16x16x32_bf16 v[22:25], v[134:137], v[212:215], v[22:25]
	v_mfma_f32_16x16x32_bf16 v[14:17], v[142:145], v[212:215], v[14:17]
	s_setprio 0
	s_setprio 1
	v_mfma_f32_16x16x32_bf16 v[50:53], v[146:149], v[184:187], v[50:53]
	v_mfma_f32_16x16x32_bf16 v[42:45], v[166:169], v[184:187], v[42:45]
	v_mfma_f32_16x16x32_bf16 v[34:37], v[146:149], v[192:195], v[34:37]
	v_mfma_f32_16x16x32_bf16 v[26:29], v[166:169], v[192:195], v[26:29]
	v_mfma_f32_16x16x32_bf16 v[18:21], v[146:149], v[200:203], v[18:21]
	v_mfma_f32_16x16x32_bf16 v[10:13], v[166:169], v[200:203], v[10:13]
	v_mfma_f32_16x16x32_bf16 v[6:9], v[146:149], v[208:211], v[6:9]
	v_mfma_f32_16x16x32_bf16 v[2:5], v[166:169], v[208:211], v[2:5]
	v_mfma_f32_16x16x32_bf16 v[50:53], v[150:153], v[188:191], v[50:53]
	v_mfma_f32_16x16x32_bf16 v[42:45], v[178:181], v[188:191], v[42:45]
	v_mfma_f32_16x16x32_bf16 v[34:37], v[150:153], v[196:199], v[34:37]
	v_mfma_f32_16x16x32_bf16 v[26:29], v[178:181], v[196:199], v[26:29]
	v_mfma_f32_16x16x32_bf16 v[18:21], v[150:153], v[204:207], v[18:21]
	v_mfma_f32_16x16x32_bf16 v[10:13], v[178:181], v[204:207], v[10:13]
	v_mfma_f32_16x16x32_bf16 v[6:9], v[150:153], v[212:215], v[6:9]
	v_mfma_f32_16x16x32_bf16 v[2:5], v[178:181], v[212:215], v[2:5]
	s_setprio 0
	s_barrier
	s_add_i32 s87, s87, 2
	s_add_u32 s24, s24, 0x100
	s_addc_u32 s25, s25, 0
	s_add_u32 s85, s85, 0x100
	s_addc_u32 s86, s86, 0
	s_cmp_gt_u32 s87, 5
	s_cbranch_scc0 .LBB0_945
	s_and_b64 vcc, exec, s[14:15]
	s_cbranch_vccz .LBB0_948
	s_barrier
.LBB0_948:
	v_mov_b32_e32 v130, v1
	v_mov_b32_e32 v132, v172
	s_lshl_b32 s8, s30, 1
	v_add_u32_e32 v133, s39, v130
	v_mov_b64_e32 v[130:131], s[48:49]
	v_mad_i64_i32 v[130:131], s[24:25], v133, s41, v[130:131]
	v_lshl_add_u64 v[130:131], v[130:131], 0, s[8:9]
	s_mov_b32 s17, s9
	v_lshlrev_b32_e32 v132, 3, v132
	v_lshl_add_u64 v[130:131], v[130:131], 0, s[16:17]
	v_ashrrev_i32_e32 v133, 31, v132
	v_lshl_add_u64 v[130:131], v[132:133], 1, v[130:131]
	v_lshl_add_u64 v[166:167], v[130:131], 0, s[18:19]
	s_lshl_b32 s8, s84, 10
	v_lshl_add_u64 v[130:131], s[8:9], 1, v[166:167]
	s_mov_b32 s101, 0
	s_mov_b32 s100, 0x32000
	v_lshl_add_u64 v[132:133], v[130:131], 0, s[100:101]
	s_mov_b32 s100, 0x64000
	v_lshl_add_u64 v[134:135], v[130:131], 0, s[100:101]
	s_mov_b32 s100, 0x96000
	v_lshl_add_u64 v[136:137], v[130:131], 0, s[100:101]
	s_mov_b32 s100, 0x190000
	v_lshl_add_u64 v[138:139], v[130:131], 0, s[100:101]
	s_mov_b32 s100, 0x1c2000
	v_lshl_add_u64 v[140:141], v[130:131], 0, s[100:101]
	s_mov_b32 s100, 0x1f4000
	v_lshl_add_u64 v[142:143], v[130:131], 0, s[100:101]
	s_mov_b32 s100, 0x226000
	v_lshl_add_u64 v[144:145], v[130:131], 0, s[100:101]
	s_mov_b32 s100, 0x0d800000
	s_cmp_eq_u32 s84, 2
	s_cbranch_scc1 .Lup3_final
	global_load_dwordx4 v[184:187], v[130:131], off
	global_load_dwordx4 v[188:191], v[130:131], off offset:256
	global_load_dwordx4 v[192:195], v[130:131], off offset:2048
	global_load_dwordx4 v[196:199], v[130:131], off offset:2304
	global_load_dwordx4 v[200:203], v[132:133], off
	global_load_dwordx4 v[204:207], v[132:133], off offset:256
	global_load_dwordx4 v[208:211], v[132:133], off offset:2048
	global_load_dwordx4 v[212:215], v[132:133], off offset:2304
	global_load_dwordx4 v[216:219], v[134:135], off
	global_load_dwordx4 v[220:223], v[134:135], off offset:256
	global_load_dwordx4 v[224:227], v[134:135], off offset:2048
	global_load_dwordx4 v[228:231], v[134:135], off offset:2304
	s_waitcnt vmcnt(8)
; DI float bflo(unsigned w) { return __uint_as_float(w << 16); }
; DI float bfhi(unsigned w) { return __uint_as_float(w & 0xffff0000u); }
;     DI void operator()(Acc& acc, const Unit& u, int wr, int wc, int fr, int fq) const {
;     ...
;         bf16_t* base = proj + (size_t)(u.pm * 256 + wr * 64 + fr) * NPJ + C_GL + u.pn * 256 + wc * 32 + fq * 8;
;         {
;             u32x4 g[2][4][2];
; #pragma unroll
;             for (int ai = 0; ai < 2; ++ai)
; #pragma unroll
;                 for (int m = 0; m < 4; ++m)
; #pragma unroll
;                     for (int bj = 0; bj < 2; ++bj) g[ai][m][bj] = *(const u32x4*)(base + (size_t)(ai * 128 + m * 16) * NPJ + u.k * 1024 + bj * 128);
; #pragma unroll
;             for (int ai = 0; ai < 2; ++ai)
; #pragma unroll
;                 for (int m = 0; m < 4; ++m)
; #pragma unroll
;                     for (int bj = 0; bj < 2; ++bj) { const u32x4 q = g[ai][m][bj]; f32x4& v0 = acc[ai][bj][m][0]; f32x4& v1 = acc[ai][bj][m][1];
;                         v0[0] *= bflo(q.x); v0[1] *= bfhi(q.x); v0[2] *= bflo(q.y); v0[3] *= bfhi(q.y); v1[0] *= bflo(q.z); v1[1] *= bfhi(q.z); v1[2] *= bflo(q.w); v1[3] *= bfhi(q.w); }
	v_lshlrev_b32_e32 v146, 16, v184
	v_and_b32_e32 v147, 0xffff0000, v184
	v_lshlrev_b32_e32 v148, 16, v192
	v_and_b32_e32 v149, 0xffff0000, v192
	v_lshlrev_b32_e32 v150, 16, v185
	v_and_b32_e32 v151, 0xffff0000, v185
	v_lshlrev_b32_e32 v152, 16, v193
	v_and_b32_e32 v153, 0xffff0000, v193
	v_max_f32_e32 v148, s100, v148
	v_max_f32_e32 v149, s100, v149
	v_max_f32_e32 v146, s100, v146
	v_max_f32_e32 v147, s100, v147
	v_max_f32_e32 v152, s100, v152
	v_max_f32_e32 v153, s100, v153
	v_max_f32_e32 v150, s100, v150
	v_max_f32_e32 v151, s100, v151
	v_rcp_f32_e32 v148, v148
	v_rcp_f32_e32 v149, v149
	v_rcp_f32_e32 v152, v152
	v_rcp_f32_e32 v153, v153
	s_nop 0
	v_pk_mul_f32 v[146:147], v[146:147], v[148:149]
	v_pk_mul_f32 v[150:151], v[150:151], v[152:153]
	v_pk_mul_f32 v[126:127], v[126:127], v[146:147]
	v_pk_mul_f32 v[128:129], v[128:129], v[150:151]
	v_lshlrev_b32_e32 v168, 16, v186
	v_and_b32_e32 v169, 0xffff0000, v186
	v_lshlrev_b32_e32 v178, 16, v194
	v_and_b32_e32 v179, 0xffff0000, v194
	v_lshlrev_b32_e32 v180, 16, v187
	v_and_b32_e32 v181, 0xffff0000, v187
	v_lshlrev_b32_e32 v244, 16, v195
	v_and_b32_e32 v245, 0xffff0000, v195
	v_max_f32_e32 v178, s100, v178
	v_max_f32_e32 v179, s100, v179
	v_max_f32_e32 v168, s100, v168
	v_max_f32_e32 v169, s100, v169
	v_max_f32_e32 v244, s100, v244
	v_max_f32_e32 v245, s100, v245
	v_max_f32_e32 v180, s100, v180
	v_max_f32_e32 v181, s100, v181
	v_rcp_f32_e32 v178, v178
	v_rcp_f32_e32 v179, v179
	v_rcp_f32_e32 v244, v244
	v_rcp_f32_e32 v245, v245
	s_nop 0
	v_pk_mul_f32 v[168:169], v[168:169], v[178:179]
	v_pk_mul_f32 v[180:181], v[180:181], v[244:245]
	v_pk_mul_f32 v[122:123], v[122:123], v[168:169]
	v_pk_mul_f32 v[124:125], v[124:125], v[180:181]
	v_lshlrev_b32_e32 v168, 16, v188
	v_and_b32_e32 v169, 0xffff0000, v188
	v_lshlrev_b32_e32 v178, 16, v196
	v_and_b32_e32 v179, 0xffff0000, v196
	v_lshlrev_b32_e32 v180, 16, v189
	v_and_b32_e32 v181, 0xffff0000, v189
	v_lshlrev_b32_e32 v244, 16, v197
	v_and_b32_e32 v245, 0xffff0000, v197
	v_max_f32_e32 v178, s100, v178
	v_max_f32_e32 v179, s100, v179
	v_max_f32_e32 v168, s100, v168
	v_max_f32_e32 v169, s100, v169
	v_max_f32_e32 v244, s100, v244
	v_max_f32_e32 v245, s100, v245
	v_max_f32_e32 v180, s100, v180
	v_max_f32_e32 v181, s100, v181
	v_rcp_f32_e32 v178, v178
	v_rcp_f32_e32 v179, v179
	v_rcp_f32_e32 v244, v244
	v_rcp_f32_e32 v245, v245
	s_nop 0
	v_pk_mul_f32 v[168:169], v[168:169], v[178:179]
	v_pk_mul_f32 v[180:181], v[180:181], v[244:245]
	v_pk_mul_f32 v[114:115], v[114:115], v[168:169]
	v_pk_mul_f32 v[116:117], v[116:117], v[180:181]
	v_lshlrev_b32_e32 v146, 16, v190
	v_and_b32_e32 v147, 0xffff0000, v190
	v_lshlrev_b32_e32 v148, 16, v198
	v_and_b32_e32 v149, 0xffff0000, v198
	v_lshlrev_b32_e32 v150, 16, v191
	v_and_b32_e32 v151, 0xffff0000, v191
	v_lshlrev_b32_e32 v152, 16, v199
	v_and_b32_e32 v153, 0xffff0000, v199
	v_max_f32_e32 v148, s100, v148
	v_max_f32_e32 v149, s100, v149
	v_max_f32_e32 v146, s100, v146
	v_max_f32_e32 v147, s100, v147
	v_max_f32_e32 v152, s100, v152
	v_max_f32_e32 v153, s100, v153
	v_max_f32_e32 v150, s100, v150
	v_max_f32_e32 v151, s100, v151
	v_rcp_f32_e32 v148, v148
	v_rcp_f32_e32 v149, v149
	v_rcp_f32_e32 v152, v152
	v_rcp_f32_e32 v153, v153
	s_nop 0
	v_pk_mul_f32 v[146:147], v[146:147], v[148:149]
	v_pk_mul_f32 v[150:151], v[150:151], v[152:153]
	v_pk_mul_f32 v[110:111], v[110:111], v[146:147]
	v_pk_mul_f32 v[112:113], v[112:113], v[150:151]
	global_load_dwordx4 v[184:187], v[136:137], off
	global_load_dwordx4 v[188:191], v[136:137], off offset:256
	global_load_dwordx4 v[192:195], v[136:137], off offset:2048
	global_load_dwordx4 v[196:199], v[136:137], off offset:2304
	s_waitcnt vmcnt(8)
	v_lshlrev_b32_e32 v146, 16, v200
	v_and_b32_e32 v147, 0xffff0000, v200
	v_lshlrev_b32_e32 v148, 16, v208
	v_and_b32_e32 v149, 0xffff0000, v208
	v_lshlrev_b32_e32 v150, 16, v201
	v_and_b32_e32 v151, 0xffff0000, v201
	v_lshlrev_b32_e32 v152, 16, v209
	v_and_b32_e32 v153, 0xffff0000, v209
	v_max_f32_e32 v148, s100, v148
	v_max_f32_e32 v149, s100, v149
	v_max_f32_e32 v146, s100, v146
	v_max_f32_e32 v147, s100, v147
	v_max_f32_e32 v152, s100, v152
	v_max_f32_e32 v153, s100, v153
	v_max_f32_e32 v150, s100, v150
	v_max_f32_e32 v151, s100, v151
	v_rcp_f32_e32 v148, v148
	v_rcp_f32_e32 v149, v149
	v_rcp_f32_e32 v152, v152
	v_rcp_f32_e32 v153, v153
	s_nop 0
	v_pk_mul_f32 v[146:147], v[146:147], v[148:149]
	v_pk_mul_f32 v[150:151], v[150:151], v[152:153]
	v_pk_mul_f32 v[118:119], v[118:119], v[146:147]
	v_pk_mul_f32 v[120:121], v[120:121], v[150:151]
	v_lshlrev_b32_e32 v168, 16, v202
	v_and_b32_e32 v169, 0xffff0000, v202
	v_lshlrev_b32_e32 v178, 16, v210
	v_and_b32_e32 v179, 0xffff0000, v210
	v_lshlrev_b32_e32 v180, 16, v203
	v_and_b32_e32 v181, 0xffff0000, v203
	v_lshlrev_b32_e32 v244, 16, v211
	v_and_b32_e32 v245, 0xffff0000, v211
	v_max_f32_e32 v178, s100, v178
	v_max_f32_e32 v179, s100, v179
	v_max_f32_e32 v168, s100, v168
	v_max_f32_e32 v169, s100, v169
	v_max_f32_e32 v244, s100, v244
	v_max_f32_e32 v245, s100, v245
	v_max_f32_e32 v180, s100, v180
	v_max_f32_e32 v181, s100, v181
	v_rcp_f32_e32 v178, v178
	v_rcp_f32_e32 v179, v179
	v_rcp_f32_e32 v244, v244
	v_rcp_f32_e32 v245, v245
	s_nop 0
	v_pk_mul_f32 v[168:169], v[168:169], v[178:179]
	v_pk_mul_f32 v[180:181], v[180:181], v[244:245]
	v_pk_mul_f32 v[106:107], v[106:107], v[168:169]
	v_pk_mul_f32 v[108:109], v[108:109], v[180:181]
	v_lshlrev_b32_e32 v168, 16, v204
	v_and_b32_e32 v169, 0xffff0000, v204
	v_lshlrev_b32_e32 v178, 16, v212
	v_and_b32_e32 v179, 0xffff0000, v212
	v_lshlrev_b32_e32 v180, 16, v205
	v_and_b32_e32 v181, 0xffff0000, v205
	v_lshlrev_b32_e32 v244, 16, v213
	v_and_b32_e32 v245, 0xffff0000, v213
; DI float bflo(unsigned w) { return __uint_as_float(w << 16); }
; DI float bfhi(unsigned w) { return __uint_as_float(w & 0xffff0000u); }
;     DI void operator()(Acc& acc, const Unit& u, int wr, int wc, int fr, int fq) const {
;     ...
;         bf16_t* base = proj + (size_t)(u.pm * 256 + wr * 64 + fr) * NPJ + C_GL + u.pn * 256 + wc * 32 + fq * 8;
;         {
;             u32x4 g[2][4][2];
; #pragma unroll
;             for (int ai = 0; ai < 2; ++ai)
; #pragma unroll
;                 for (int m = 0; m < 4; ++m)
; #pragma unroll
;                     for (int bj = 0; bj < 2; ++bj) g[ai][m][bj] = *(const u32x4*)(base + (size_t)(ai * 128 + m * 16) * NPJ + u.k * 1024 + bj * 128);
; #pragma unroll
;             for (int ai = 0; ai < 2; ++ai)
; #pragma unroll
;                 for (int m = 0; m < 4; ++m)
; #pragma unroll
;                     for (int bj = 0; bj < 2; ++bj) { const u32x4 q = g[ai][m][bj]; f32x4& v0 = acc[ai][bj][m][0]; f32x4& v1 = acc[ai][bj][m][1];
;                         v0[0] *= bflo(q.x); v0[1] *= bfhi(q.x); v0[2] *= bflo(q.y); v0[3] *= bfhi(q.y); v1[0] *= bflo(q.z); v1[1] *= bfhi(q.z); v1[2] *= bflo(q.w); v1[3] *= bfhi(q.w); }
	v_max_f32_e32 v178, s100, v178
	v_max_f32_e32 v179, s100, v179
	v_max_f32_e32 v168, s100, v168
	v_max_f32_e32 v169, s100, v169
	v_max_f32_e32 v244, s100, v244
	v_max_f32_e32 v245, s100, v245
	v_max_f32_e32 v180, s100, v180
	v_max_f32_e32 v181, s100, v181
	v_rcp_f32_e32 v178, v178
	v_rcp_f32_e32 v179, v179
	v_rcp_f32_e32 v244, v244
	v_rcp_f32_e32 v245, v245
	s_nop 0
	v_pk_mul_f32 v[168:169], v[168:169], v[178:179]
	v_pk_mul_f32 v[180:181], v[180:181], v[244:245]
	v_pk_mul_f32 v[98:99], v[98:99], v[168:169]
	v_pk_mul_f32 v[100:101], v[100:101], v[180:181]
	v_lshlrev_b32_e32 v146, 16, v206
	v_and_b32_e32 v147, 0xffff0000, v206
	v_lshlrev_b32_e32 v148, 16, v214
	v_and_b32_e32 v149, 0xffff0000, v214
	v_lshlrev_b32_e32 v150, 16, v207
	v_and_b32_e32 v151, 0xffff0000, v207
	v_lshlrev_b32_e32 v152, 16, v215
	v_and_b32_e32 v153, 0xffff0000, v215
	v_max_f32_e32 v148, s100, v148
	v_max_f32_e32 v149, s100, v149
	v_max_f32_e32 v146, s100, v146
	v_max_f32_e32 v147, s100, v147
	v_max_f32_e32 v152, s100, v152
	v_max_f32_e32 v153, s100, v153
	v_max_f32_e32 v150, s100, v150
	v_max_f32_e32 v151, s100, v151
	v_rcp_f32_e32 v148, v148
	v_rcp_f32_e32 v149, v149
	v_rcp_f32_e32 v152, v152
	v_rcp_f32_e32 v153, v153
	s_nop 0
	v_pk_mul_f32 v[146:147], v[146:147], v[148:149]
	v_pk_mul_f32 v[150:151], v[150:151], v[152:153]
	v_pk_mul_f32 v[90:91], v[90:91], v[146:147]
	v_pk_mul_f32 v[92:93], v[92:93], v[150:151]
	global_load_dwordx4 v[200:203], v[138:139], off
	global_load_dwordx4 v[204:207], v[138:139], off offset:256
	global_load_dwordx4 v[208:211], v[138:139], off offset:2048
	global_load_dwordx4 v[212:215], v[138:139], off offset:2304
	s_waitcnt vmcnt(8)
	v_lshlrev_b32_e32 v146, 16, v216
	v_and_b32_e32 v147, 0xffff0000, v216
	v_lshlrev_b32_e32 v148, 16, v224
	v_and_b32_e32 v149, 0xffff0000, v224
	v_lshlrev_b32_e32 v150, 16, v217
	v_and_b32_e32 v151, 0xffff0000, v217
	v_lshlrev_b32_e32 v152, 16, v225
	v_and_b32_e32 v153, 0xffff0000, v225
	v_max_f32_e32 v148, s100, v148
	v_max_f32_e32 v149, s100, v149
	v_max_f32_e32 v146, s100, v146
	v_max_f32_e32 v147, s100, v147
	v_max_f32_e32 v152, s100, v152
	v_max_f32_e32 v153, s100, v153
	v_max_f32_e32 v150, s100, v150
	v_max_f32_e32 v151, s100, v151
	v_rcp_f32_e32 v148, v148
	v_rcp_f32_e32 v149, v149
	v_rcp_f32_e32 v152, v152
	v_rcp_f32_e32 v153, v153
	s_nop 0
	v_pk_mul_f32 v[146:147], v[146:147], v[148:149]
	v_pk_mul_f32 v[150:151], v[150:151], v[152:153]
	v_pk_mul_f32 v[102:103], v[102:103], v[146:147]
	v_pk_mul_f32 v[104:105], v[104:105], v[150:151]
	v_lshlrev_b32_e32 v168, 16, v218
	v_and_b32_e32 v169, 0xffff0000, v218
	v_lshlrev_b32_e32 v178, 16, v226
	v_and_b32_e32 v179, 0xffff0000, v226
	v_lshlrev_b32_e32 v180, 16, v219
	v_and_b32_e32 v181, 0xffff0000, v219
	v_lshlrev_b32_e32 v244, 16, v227
	v_and_b32_e32 v245, 0xffff0000, v227
	v_max_f32_e32 v178, s100, v178
	v_max_f32_e32 v179, s100, v179
	v_max_f32_e32 v168, s100, v168
	v_max_f32_e32 v169, s100, v169
	v_max_f32_e32 v244, s100, v244
	v_max_f32_e32 v245, s100, v245
	v_max_f32_e32 v180, s100, v180
	v_max_f32_e32 v181, s100, v181
	v_rcp_f32_e32 v178, v178
	v_rcp_f32_e32 v179, v179
	v_rcp_f32_e32 v244, v244
	v_rcp_f32_e32 v245, v245
	s_nop 0
	v_pk_mul_f32 v[168:169], v[168:169], v[178:179]
	v_pk_mul_f32 v[180:181], v[180:181], v[244:245]
	v_pk_mul_f32 v[94:95], v[94:95], v[168:169]
	v_pk_mul_f32 v[96:97], v[96:97], v[180:181]
	v_lshlrev_b32_e32 v168, 16, v220
	v_and_b32_e32 v169, 0xffff0000, v220
	v_lshlrev_b32_e32 v178, 16, v228
	v_and_b32_e32 v179, 0xffff0000, v228
	v_lshlrev_b32_e32 v180, 16, v221
	v_and_b32_e32 v181, 0xffff0000, v221
	v_lshlrev_b32_e32 v244, 16, v229
	v_and_b32_e32 v245, 0xffff0000, v229
	v_max_f32_e32 v178, s100, v178
	v_max_f32_e32 v179, s100, v179
	v_max_f32_e32 v168, s100, v168
	v_max_f32_e32 v169, s100, v169
	v_max_f32_e32 v244, s100, v244
	v_max_f32_e32 v245, s100, v245
	v_max_f32_e32 v180, s100, v180
	v_max_f32_e32 v181, s100, v181
	v_rcp_f32_e32 v178, v178
	v_rcp_f32_e32 v179, v179
	v_rcp_f32_e32 v244, v244
	v_rcp_f32_e32 v245, v245
	s_nop 0
	v_pk_mul_f32 v[168:169], v[168:169], v[178:179]
	v_pk_mul_f32 v[180:181], v[180:181], v[244:245]
	v_pk_mul_f32 v[82:83], v[82:83], v[168:169]
	v_pk_mul_f32 v[84:85], v[84:85], v[180:181]
	v_lshlrev_b32_e32 v146, 16, v222
	v_and_b32_e32 v147, 0xffff0000, v222
	v_lshlrev_b32_e32 v148, 16, v230
	v_and_b32_e32 v149, 0xffff0000, v230
	v_lshlrev_b32_e32 v150, 16, v223
	v_and_b32_e32 v151, 0xffff0000, v223
	v_lshlrev_b32_e32 v152, 16, v231
	v_and_b32_e32 v153, 0xffff0000, v231
	v_max_f32_e32 v148, s100, v148
	v_max_f32_e32 v149, s100, v149
	v_max_f32_e32 v146, s100, v146
	v_max_f32_e32 v147, s100, v147
	v_max_f32_e32 v152, s100, v152
	v_max_f32_e32 v153, s100, v153
	v_max_f32_e32 v150, s100, v150
	v_max_f32_e32 v151, s100, v151
	v_rcp_f32_e32 v148, v148
	v_rcp_f32_e32 v149, v149
	v_rcp_f32_e32 v152, v152
	v_rcp_f32_e32 v153, v153
	s_nop 0
	v_pk_mul_f32 v[146:147], v[146:147], v[148:149]
	v_pk_mul_f32 v[150:151], v[150:151], v[152:153]
	v_pk_mul_f32 v[74:75], v[74:75], v[146:147]
	v_pk_mul_f32 v[76:77], v[76:77], v[150:151]
	global_load_dwordx4 v[216:219], v[140:141], off
	global_load_dwordx4 v[220:223], v[140:141], off offset:256
	global_load_dwordx4 v[224:227], v[140:141], off offset:2048
	global_load_dwordx4 v[228:231], v[140:141], off offset:2304
	s_waitcnt vmcnt(8)
; DI float bflo(unsigned w) { return __uint_as_float(w << 16); }
; DI float bfhi(unsigned w) { return __uint_as_float(w & 0xffff0000u); }
;     DI void operator()(Acc& acc, const Unit& u, int wr, int wc, int fr, int fq) const {
;     ...
;         bf16_t* base = proj + (size_t)(u.pm * 256 + wr * 64 + fr) * NPJ + C_GL + u.pn * 256 + wc * 32 + fq * 8;
;         {
;             u32x4 g[2][4][2];
; #pragma unroll
;             for (int ai = 0; ai < 2; ++ai)
; #pragma unroll
;                 for (int m = 0; m < 4; ++m)
; #pragma unroll
;                     for (int bj = 0; bj < 2; ++bj) g[ai][m][bj] = *(const u32x4*)(base + (size_t)(ai * 128 + m * 16) * NPJ + u.k * 1024 + bj * 128);
; #pragma unroll
;             for (int ai = 0; ai < 2; ++ai)
; #pragma unroll
;                 for (int m = 0; m < 4; ++m)
; #pragma unroll
;                     for (int bj = 0; bj < 2; ++bj) { const u32x4 q = g[ai][m][bj]; f32x4& v0 = acc[ai][bj][m][0]; f32x4& v1 = acc[ai][bj][m][1];
;                         v0[0] *= bflo(q.x); v0[1] *= bfhi(q.x); v0[2] *= bflo(q.y); v0[3] *= bfhi(q.y); v1[0] *= bflo(q.z); v1[1] *= bfhi(q.z); v1[2] *= bflo(q.w); v1[3] *= bfhi(q.w); }
	v_lshlrev_b32_e32 v146, 16, v184
	v_and_b32_e32 v147, 0xffff0000, v184
	v_lshlrev_b32_e32 v148, 16, v192
	v_and_b32_e32 v149, 0xffff0000, v192
	v_lshlrev_b32_e32 v150, 16, v185
	v_and_b32_e32 v151, 0xffff0000, v185
	v_lshlrev_b32_e32 v152, 16, v193
	v_and_b32_e32 v153, 0xffff0000, v193
	v_max_f32_e32 v148, s100, v148
	v_max_f32_e32 v149, s100, v149
	v_max_f32_e32 v146, s100, v146
	v_max_f32_e32 v147, s100, v147
	v_max_f32_e32 v152, s100, v152
	v_max_f32_e32 v153, s100, v153
	v_max_f32_e32 v150, s100, v150
	v_max_f32_e32 v151, s100, v151
	v_rcp_f32_e32 v148, v148
	v_rcp_f32_e32 v149, v149
	v_rcp_f32_e32 v152, v152
	v_rcp_f32_e32 v153, v153
	s_nop 0
	v_pk_mul_f32 v[146:147], v[146:147], v[148:149]
	v_pk_mul_f32 v[150:151], v[150:151], v[152:153]
	v_pk_mul_f32 v[86:87], v[86:87], v[146:147]
	v_pk_mul_f32 v[88:89], v[88:89], v[150:151]
	v_lshlrev_b32_e32 v168, 16, v186
	v_and_b32_e32 v169, 0xffff0000, v186
	v_lshlrev_b32_e32 v178, 16, v194
	v_and_b32_e32 v179, 0xffff0000, v194
	v_lshlrev_b32_e32 v180, 16, v187
	v_and_b32_e32 v181, 0xffff0000, v187
	v_lshlrev_b32_e32 v244, 16, v195
	v_and_b32_e32 v245, 0xffff0000, v195
	v_max_f32_e32 v178, s100, v178
	v_max_f32_e32 v179, s100, v179
	v_max_f32_e32 v168, s100, v168
	v_max_f32_e32 v169, s100, v169
	v_max_f32_e32 v244, s100, v244
	v_max_f32_e32 v245, s100, v245
	v_max_f32_e32 v180, s100, v180
	v_max_f32_e32 v181, s100, v181
	v_rcp_f32_e32 v178, v178
	v_rcp_f32_e32 v179, v179
	v_rcp_f32_e32 v244, v244
	v_rcp_f32_e32 v245, v245
	s_nop 0
	v_pk_mul_f32 v[168:169], v[168:169], v[178:179]
	v_pk_mul_f32 v[180:181], v[180:181], v[244:245]
	v_pk_mul_f32 v[78:79], v[78:79], v[168:169]
	v_pk_mul_f32 v[80:81], v[80:81], v[180:181]
	v_lshlrev_b32_e32 v168, 16, v188
	v_and_b32_e32 v169, 0xffff0000, v188
	v_lshlrev_b32_e32 v178, 16, v196
	v_and_b32_e32 v179, 0xffff0000, v196
	v_lshlrev_b32_e32 v180, 16, v189
	v_and_b32_e32 v181, 0xffff0000, v189
	v_lshlrev_b32_e32 v244, 16, v197
	v_and_b32_e32 v245, 0xffff0000, v197
	v_max_f32_e32 v178, s100, v178
	v_max_f32_e32 v179, s100, v179
	v_max_f32_e32 v168, s100, v168
	v_max_f32_e32 v169, s100, v169
	v_max_f32_e32 v244, s100, v244
	v_max_f32_e32 v245, s100, v245
	v_max_f32_e32 v180, s100, v180
	v_max_f32_e32 v181, s100, v181
	v_rcp_f32_e32 v178, v178
	v_rcp_f32_e32 v179, v179
	v_rcp_f32_e32 v244, v244
	v_rcp_f32_e32 v245, v245
	s_nop 0
	v_pk_mul_f32 v[168:169], v[168:169], v[178:179]
	v_pk_mul_f32 v[180:181], v[180:181], v[244:245]
	v_pk_mul_f32 v[70:71], v[70:71], v[168:169]
	v_pk_mul_f32 v[72:73], v[72:73], v[180:181]
	v_lshlrev_b32_e32 v146, 16, v190
	v_and_b32_e32 v147, 0xffff0000, v190
	v_lshlrev_b32_e32 v148, 16, v198
	v_and_b32_e32 v149, 0xffff0000, v198
	v_lshlrev_b32_e32 v150, 16, v191
	v_and_b32_e32 v151, 0xffff0000, v191
	v_lshlrev_b32_e32 v152, 16, v199
	v_and_b32_e32 v153, 0xffff0000, v199
	v_max_f32_e32 v148, s100, v148
	v_max_f32_e32 v149, s100, v149
	v_max_f32_e32 v146, s100, v146
	v_max_f32_e32 v147, s100, v147
	v_max_f32_e32 v152, s100, v152
	v_max_f32_e32 v153, s100, v153
	v_max_f32_e32 v150, s100, v150
	v_max_f32_e32 v151, s100, v151
	v_rcp_f32_e32 v148, v148
	v_rcp_f32_e32 v149, v149
	v_rcp_f32_e32 v152, v152
	v_rcp_f32_e32 v153, v153
	s_nop 0
	v_pk_mul_f32 v[146:147], v[146:147], v[148:149]
	v_pk_mul_f32 v[150:151], v[150:151], v[152:153]
	v_pk_mul_f32 v[66:67], v[66:67], v[146:147]
	v_pk_mul_f32 v[68:69], v[68:69], v[150:151]
	global_load_dwordx4 v[184:187], v[142:143], off
	global_load_dwordx4 v[188:191], v[142:143], off offset:256
	global_load_dwordx4 v[192:195], v[142:143], off offset:2048
	global_load_dwordx4 v[196:199], v[142:143], off offset:2304
	s_waitcnt vmcnt(8)
	v_lshlrev_b32_e32 v146, 16, v200
	v_and_b32_e32 v147, 0xffff0000, v200
	v_lshlrev_b32_e32 v148, 16, v208
	v_and_b32_e32 v149, 0xffff0000, v208
	v_lshlrev_b32_e32 v150, 16, v201
	v_and_b32_e32 v151, 0xffff0000, v201
	v_lshlrev_b32_e32 v152, 16, v209
	v_and_b32_e32 v153, 0xffff0000, v209
	v_max_f32_e32 v148, s100, v148
	v_max_f32_e32 v149, s100, v149
	v_max_f32_e32 v146, s100, v146
	v_max_f32_e32 v147, s100, v147
	v_max_f32_e32 v152, s100, v152
	v_max_f32_e32 v153, s100, v153
	v_max_f32_e32 v150, s100, v150
	v_max_f32_e32 v151, s100, v151
	v_rcp_f32_e32 v148, v148
	v_rcp_f32_e32 v149, v149
	v_rcp_f32_e32 v152, v152
	v_rcp_f32_e32 v153, v153
	s_nop 0
	v_pk_mul_f32 v[146:147], v[146:147], v[148:149]
	v_pk_mul_f32 v[150:151], v[150:151], v[152:153]
	v_pk_mul_f32 v[62:63], v[62:63], v[146:147]
	v_pk_mul_f32 v[64:65], v[64:65], v[150:151]
	v_lshlrev_b32_e32 v168, 16, v202
	v_and_b32_e32 v169, 0xffff0000, v202
	v_lshlrev_b32_e32 v178, 16, v210
	v_and_b32_e32 v179, 0xffff0000, v210
	v_lshlrev_b32_e32 v180, 16, v203
	v_and_b32_e32 v181, 0xffff0000, v203
	v_lshlrev_b32_e32 v244, 16, v211
	v_and_b32_e32 v245, 0xffff0000, v211
	v_max_f32_e32 v178, s100, v178
	v_max_f32_e32 v179, s100, v179
	v_max_f32_e32 v168, s100, v168
	v_max_f32_e32 v169, s100, v169
	v_max_f32_e32 v244, s100, v244
	v_max_f32_e32 v245, s100, v245
	v_max_f32_e32 v180, s100, v180
	v_max_f32_e32 v181, s100, v181
	v_rcp_f32_e32 v178, v178
	v_rcp_f32_e32 v179, v179
	v_rcp_f32_e32 v244, v244
	v_rcp_f32_e32 v245, v245
	s_nop 0
	v_pk_mul_f32 v[168:169], v[168:169], v[178:179]
	v_pk_mul_f32 v[180:181], v[180:181], v[244:245]
	v_pk_mul_f32 v[58:59], v[58:59], v[168:169]
	v_pk_mul_f32 v[60:61], v[60:61], v[180:181]
	v_lshlrev_b32_e32 v168, 16, v204
	v_and_b32_e32 v169, 0xffff0000, v204
	v_lshlrev_b32_e32 v178, 16, v212
	v_and_b32_e32 v179, 0xffff0000, v212
	v_lshlrev_b32_e32 v180, 16, v205
	v_and_b32_e32 v181, 0xffff0000, v205
	v_lshlrev_b32_e32 v244, 16, v213
	v_and_b32_e32 v245, 0xffff0000, v213
	v_max_f32_e32 v178, s100, v178
; DI float bflo(unsigned w) { return __uint_as_float(w << 16); }
; DI float bfhi(unsigned w) { return __uint_as_float(w & 0xffff0000u); }
;     DI void operator()(Acc& acc, const Unit& u, int wr, int wc, int fr, int fq) const {
;     ...
;         bf16_t* base = proj + (size_t)(u.pm * 256 + wr * 64 + fr) * NPJ + C_GL + u.pn * 256 + wc * 32 + fq * 8;
;         {
;             u32x4 g[2][4][2];
; #pragma unroll
;             for (int ai = 0; ai < 2; ++ai)
; #pragma unroll
;                 for (int m = 0; m < 4; ++m)
; #pragma unroll
;                     for (int bj = 0; bj < 2; ++bj) g[ai][m][bj] = *(const u32x4*)(base + (size_t)(ai * 128 + m * 16) * NPJ + u.k * 1024 + bj * 128);
; #pragma unroll
;             for (int ai = 0; ai < 2; ++ai)
; #pragma unroll
;                 for (int m = 0; m < 4; ++m)
; #pragma unroll
;                     for (int bj = 0; bj < 2; ++bj) { const u32x4 q = g[ai][m][bj]; f32x4& v0 = acc[ai][bj][m][0]; f32x4& v1 = acc[ai][bj][m][1];
;                         v0[0] *= bflo(q.x); v0[1] *= bfhi(q.x); v0[2] *= bflo(q.y); v0[3] *= bfhi(q.y); v1[0] *= bflo(q.z); v1[1] *= bfhi(q.z); v1[2] *= bflo(q.w); v1[3] *= bfhi(q.w); }
	v_max_f32_e32 v179, s100, v179
	v_max_f32_e32 v168, s100, v168
	v_max_f32_e32 v169, s100, v169
	v_max_f32_e32 v244, s100, v244
	v_max_f32_e32 v245, s100, v245
	v_max_f32_e32 v180, s100, v180
	v_max_f32_e32 v181, s100, v181
	v_rcp_f32_e32 v178, v178
	v_rcp_f32_e32 v179, v179
	v_rcp_f32_e32 v244, v244
	v_rcp_f32_e32 v245, v245
	s_nop 0
	v_pk_mul_f32 v[168:169], v[168:169], v[178:179]
	v_pk_mul_f32 v[180:181], v[180:181], v[244:245]
	v_pk_mul_f32 v[50:51], v[50:51], v[168:169]
	v_pk_mul_f32 v[52:53], v[52:53], v[180:181]
	v_lshlrev_b32_e32 v146, 16, v206
	v_and_b32_e32 v147, 0xffff0000, v206
	v_lshlrev_b32_e32 v148, 16, v214
	v_and_b32_e32 v149, 0xffff0000, v214
	v_lshlrev_b32_e32 v150, 16, v207
	v_and_b32_e32 v151, 0xffff0000, v207
	v_lshlrev_b32_e32 v152, 16, v215
	v_and_b32_e32 v153, 0xffff0000, v215
	v_max_f32_e32 v148, s100, v148
	v_max_f32_e32 v149, s100, v149
	v_max_f32_e32 v146, s100, v146
	v_max_f32_e32 v147, s100, v147
	v_max_f32_e32 v152, s100, v152
	v_max_f32_e32 v153, s100, v153
	v_max_f32_e32 v150, s100, v150
	v_max_f32_e32 v151, s100, v151
	v_rcp_f32_e32 v148, v148
	v_rcp_f32_e32 v149, v149
	v_rcp_f32_e32 v152, v152
	v_rcp_f32_e32 v153, v153
	s_nop 0
	v_pk_mul_f32 v[146:147], v[146:147], v[148:149]
	v_pk_mul_f32 v[150:151], v[150:151], v[152:153]
	v_pk_mul_f32 v[42:43], v[42:43], v[146:147]
	v_pk_mul_f32 v[44:45], v[44:45], v[150:151]
	global_load_dwordx4 v[200:203], v[144:145], off
	global_load_dwordx4 v[204:207], v[144:145], off offset:256
	global_load_dwordx4 v[208:211], v[144:145], off offset:2048
	global_load_dwordx4 v[212:215], v[144:145], off offset:2304
	s_waitcnt vmcnt(8)
	v_lshlrev_b32_e32 v146, 16, v216
	v_and_b32_e32 v147, 0xffff0000, v216
	v_lshlrev_b32_e32 v148, 16, v224
	v_and_b32_e32 v149, 0xffff0000, v224
	v_lshlrev_b32_e32 v150, 16, v217
	v_and_b32_e32 v151, 0xffff0000, v217
	v_lshlrev_b32_e32 v152, 16, v225
	v_and_b32_e32 v153, 0xffff0000, v225
	v_max_f32_e32 v148, s100, v148
	v_max_f32_e32 v149, s100, v149
	v_max_f32_e32 v146, s100, v146
	v_max_f32_e32 v147, s100, v147
	v_max_f32_e32 v152, s100, v152
	v_max_f32_e32 v153, s100, v153
	v_max_f32_e32 v150, s100, v150
	v_max_f32_e32 v151, s100, v151
	v_rcp_f32_e32 v148, v148
	v_rcp_f32_e32 v149, v149
	v_rcp_f32_e32 v152, v152
	v_rcp_f32_e32 v153, v153
	s_nop 0
	v_pk_mul_f32 v[146:147], v[146:147], v[148:149]
	v_pk_mul_f32 v[150:151], v[150:151], v[152:153]
	v_pk_mul_f32 v[54:55], v[54:55], v[146:147]
	v_pk_mul_f32 v[56:57], v[56:57], v[150:151]
	v_lshlrev_b32_e32 v168, 16, v218
	v_and_b32_e32 v169, 0xffff0000, v218
	v_lshlrev_b32_e32 v178, 16, v226
	v_and_b32_e32 v179, 0xffff0000, v226
	v_lshlrev_b32_e32 v180, 16, v219
	v_and_b32_e32 v181, 0xffff0000, v219
	v_lshlrev_b32_e32 v244, 16, v227
	v_and_b32_e32 v245, 0xffff0000, v227
	v_max_f32_e32 v178, s100, v178
	v_max_f32_e32 v179, s100, v179
	v_max_f32_e32 v168, s100, v168
	v_max_f32_e32 v169, s100, v169
	v_max_f32_e32 v244, s100, v244
	v_max_f32_e32 v245, s100, v245
	v_max_f32_e32 v180, s100, v180
	v_max_f32_e32 v181, s100, v181
	v_rcp_f32_e32 v178, v178
	v_rcp_f32_e32 v179, v179
	v_rcp_f32_e32 v244, v244
	v_rcp_f32_e32 v245, v245
	s_nop 0
	v_pk_mul_f32 v[168:169], v[168:169], v[178:179]
	v_pk_mul_f32 v[180:181], v[180:181], v[244:245]
	v_pk_mul_f32 v[46:47], v[46:47], v[168:169]
	v_pk_mul_f32 v[48:49], v[48:49], v[180:181]
	v_lshlrev_b32_e32 v168, 16, v220
	v_and_b32_e32 v169, 0xffff0000, v220
	v_lshlrev_b32_e32 v178, 16, v228
	v_and_b32_e32 v179, 0xffff0000, v228
	v_lshlrev_b32_e32 v180, 16, v221
	v_and_b32_e32 v181, 0xffff0000, v221
	v_lshlrev_b32_e32 v244, 16, v229
	v_and_b32_e32 v245, 0xffff0000, v229
	v_max_f32_e32 v178, s100, v178
	v_max_f32_e32 v179, s100, v179
	v_max_f32_e32 v168, s100, v168
	v_max_f32_e32 v169, s100, v169
	v_max_f32_e32 v244, s100, v244
	v_max_f32_e32 v245, s100, v245
	v_max_f32_e32 v180, s100, v180
	v_max_f32_e32 v181, s100, v181
	v_rcp_f32_e32 v178, v178
	v_rcp_f32_e32 v179, v179
	v_rcp_f32_e32 v244, v244
	v_rcp_f32_e32 v245, v245
	s_nop 0
	v_pk_mul_f32 v[168:169], v[168:169], v[178:179]
	v_pk_mul_f32 v[180:181], v[180:181], v[244:245]
	v_pk_mul_f32 v[34:35], v[34:35], v[168:169]
	v_pk_mul_f32 v[36:37], v[36:37], v[180:181]
	v_lshlrev_b32_e32 v146, 16, v222
	v_and_b32_e32 v147, 0xffff0000, v222
	v_lshlrev_b32_e32 v148, 16, v230
	v_and_b32_e32 v149, 0xffff0000, v230
	v_lshlrev_b32_e32 v150, 16, v223
	v_and_b32_e32 v151, 0xffff0000, v223
	v_lshlrev_b32_e32 v152, 16, v231
	v_and_b32_e32 v153, 0xffff0000, v231
	v_max_f32_e32 v148, s100, v148
	v_max_f32_e32 v149, s100, v149
	v_max_f32_e32 v146, s100, v146
	v_max_f32_e32 v147, s100, v147
	v_max_f32_e32 v152, s100, v152
	v_max_f32_e32 v153, s100, v153
	v_max_f32_e32 v150, s100, v150
	v_max_f32_e32 v151, s100, v151
	v_rcp_f32_e32 v148, v148
	v_rcp_f32_e32 v149, v149
	v_rcp_f32_e32 v152, v152
	v_rcp_f32_e32 v153, v153
	s_nop 0
	v_pk_mul_f32 v[146:147], v[146:147], v[148:149]
	v_pk_mul_f32 v[150:151], v[150:151], v[152:153]
	v_pk_mul_f32 v[26:27], v[26:27], v[146:147]
	v_pk_mul_f32 v[28:29], v[28:29], v[150:151]
	s_waitcnt vmcnt(4)
; DI float bflo(unsigned w) { return __uint_as_float(w << 16); }
; DI float bfhi(unsigned w) { return __uint_as_float(w & 0xffff0000u); }
;     DI void operator()(Acc& acc, const Unit& u, int wr, int wc, int fr, int fq) const {
;     ...
;         bf16_t* base = proj + (size_t)(u.pm * 256 + wr * 64 + fr) * NPJ + C_GL + u.pn * 256 + wc * 32 + fq * 8;
;         {
;             u32x4 g[2][4][2];
; #pragma unroll
;             for (int ai = 0; ai < 2; ++ai)
; #pragma unroll
;                 for (int m = 0; m < 4; ++m)
; #pragma unroll
;                     for (int bj = 0; bj < 2; ++bj) g[ai][m][bj] = *(const u32x4*)(base + (size_t)(ai * 128 + m * 16) * NPJ + u.k * 1024 + bj * 128);
; #pragma unroll
;             for (int ai = 0; ai < 2; ++ai)
; #pragma unroll
;                 for (int m = 0; m < 4; ++m)
; #pragma unroll
;                     for (int bj = 0; bj < 2; ++bj) { const u32x4 q = g[ai][m][bj]; f32x4& v0 = acc[ai][bj][m][0]; f32x4& v1 = acc[ai][bj][m][1];
;                         v0[0] *= bflo(q.x); v0[1] *= bfhi(q.x); v0[2] *= bflo(q.y); v0[3] *= bfhi(q.y); v1[0] *= bflo(q.z); v1[1] *= bfhi(q.z); v1[2] *= bflo(q.w); v1[3] *= bfhi(q.w); }
	v_lshlrev_b32_e32 v146, 16, v184
	v_and_b32_e32 v147, 0xffff0000, v184
	v_lshlrev_b32_e32 v148, 16, v192
	v_and_b32_e32 v149, 0xffff0000, v192
	v_lshlrev_b32_e32 v150, 16, v185
	v_and_b32_e32 v151, 0xffff0000, v185
	v_lshlrev_b32_e32 v152, 16, v193
	v_and_b32_e32 v153, 0xffff0000, v193
	v_max_f32_e32 v148, s100, v148
	v_max_f32_e32 v149, s100, v149
	v_max_f32_e32 v146, s100, v146
	v_max_f32_e32 v147, s100, v147
	v_max_f32_e32 v152, s100, v152
	v_max_f32_e32 v153, s100, v153
	v_max_f32_e32 v150, s100, v150
	v_max_f32_e32 v151, s100, v151
	v_rcp_f32_e32 v148, v148
	v_rcp_f32_e32 v149, v149
	v_rcp_f32_e32 v152, v152
	v_rcp_f32_e32 v153, v153
	s_nop 0
	v_pk_mul_f32 v[146:147], v[146:147], v[148:149]
	v_pk_mul_f32 v[150:151], v[150:151], v[152:153]
	v_pk_mul_f32 v[38:39], v[38:39], v[146:147]
	v_pk_mul_f32 v[40:41], v[40:41], v[150:151]
	v_lshlrev_b32_e32 v168, 16, v186
	v_and_b32_e32 v169, 0xffff0000, v186
	v_lshlrev_b32_e32 v178, 16, v194
	v_and_b32_e32 v179, 0xffff0000, v194
	v_lshlrev_b32_e32 v180, 16, v187
	v_and_b32_e32 v181, 0xffff0000, v187
	v_lshlrev_b32_e32 v244, 16, v195
	v_and_b32_e32 v245, 0xffff0000, v195
	v_max_f32_e32 v178, s100, v178
	v_max_f32_e32 v179, s100, v179
	v_max_f32_e32 v168, s100, v168
	v_max_f32_e32 v169, s100, v169
	v_max_f32_e32 v244, s100, v244
	v_max_f32_e32 v245, s100, v245
	v_max_f32_e32 v180, s100, v180
	v_max_f32_e32 v181, s100, v181
	v_rcp_f32_e32 v178, v178
	v_rcp_f32_e32 v179, v179
	v_rcp_f32_e32 v244, v244
	v_rcp_f32_e32 v245, v245
	s_nop 0
	v_pk_mul_f32 v[168:169], v[168:169], v[178:179]
	v_pk_mul_f32 v[180:181], v[180:181], v[244:245]
	v_pk_mul_f32 v[30:31], v[30:31], v[168:169]
	v_pk_mul_f32 v[32:33], v[32:33], v[180:181]
	v_lshlrev_b32_e32 v168, 16, v188
	v_and_b32_e32 v169, 0xffff0000, v188
	v_lshlrev_b32_e32 v178, 16, v196
	v_and_b32_e32 v179, 0xffff0000, v196
	v_lshlrev_b32_e32 v180, 16, v189
	v_and_b32_e32 v181, 0xffff0000, v189
	v_lshlrev_b32_e32 v244, 16, v197
	v_and_b32_e32 v245, 0xffff0000, v197
	v_max_f32_e32 v178, s100, v178
	v_max_f32_e32 v179, s100, v179
	v_max_f32_e32 v168, s100, v168
	v_max_f32_e32 v169, s100, v169
	v_max_f32_e32 v244, s100, v244
	v_max_f32_e32 v245, s100, v245
	v_max_f32_e32 v180, s100, v180
	v_max_f32_e32 v181, s100, v181
	v_rcp_f32_e32 v178, v178
	v_rcp_f32_e32 v179, v179
	v_rcp_f32_e32 v244, v244
	v_rcp_f32_e32 v245, v245
	s_nop 0
	v_pk_mul_f32 v[168:169], v[168:169], v[178:179]
	v_pk_mul_f32 v[180:181], v[180:181], v[244:245]
	v_pk_mul_f32 v[18:19], v[18:19], v[168:169]
	v_pk_mul_f32 v[20:21], v[20:21], v[180:181]
	v_lshlrev_b32_e32 v146, 16, v190
	v_and_b32_e32 v147, 0xffff0000, v190
	v_lshlrev_b32_e32 v148, 16, v198
	v_and_b32_e32 v149, 0xffff0000, v198
	v_lshlrev_b32_e32 v150, 16, v191
	v_and_b32_e32 v151, 0xffff0000, v191
	v_lshlrev_b32_e32 v152, 16, v199
	v_and_b32_e32 v153, 0xffff0000, v199
	v_max_f32_e32 v148, s100, v148
	v_max_f32_e32 v149, s100, v149
	v_max_f32_e32 v146, s100, v146
	v_max_f32_e32 v147, s100, v147
	v_max_f32_e32 v152, s100, v152
	v_max_f32_e32 v153, s100, v153
	v_max_f32_e32 v150, s100, v150
	v_max_f32_e32 v151, s100, v151
	v_rcp_f32_e32 v148, v148
	v_rcp_f32_e32 v149, v149
	v_rcp_f32_e32 v152, v152
	v_rcp_f32_e32 v153, v153
	s_nop 0
	v_pk_mul_f32 v[146:147], v[146:147], v[148:149]
	v_pk_mul_f32 v[150:151], v[150:151], v[152:153]
	v_pk_mul_f32 v[10:11], v[10:11], v[146:147]
	v_pk_mul_f32 v[12:13], v[12:13], v[150:151]
	s_waitcnt vmcnt(0)
	v_lshlrev_b32_e32 v146, 16, v200
	v_and_b32_e32 v147, 0xffff0000, v200
	v_lshlrev_b32_e32 v148, 16, v208
	v_and_b32_e32 v149, 0xffff0000, v208
	v_lshlrev_b32_e32 v150, 16, v201
	v_and_b32_e32 v151, 0xffff0000, v201
	v_lshlrev_b32_e32 v152, 16, v209
	v_and_b32_e32 v153, 0xffff0000, v209
	v_max_f32_e32 v148, s100, v148
	v_max_f32_e32 v149, s100, v149
	v_max_f32_e32 v146, s100, v146
	v_max_f32_e32 v147, s100, v147
	v_max_f32_e32 v152, s100, v152
	v_max_f32_e32 v153, s100, v153
	v_max_f32_e32 v150, s100, v150
	v_max_f32_e32 v151, s100, v151
	v_rcp_f32_e32 v148, v148
	v_rcp_f32_e32 v149, v149
	v_rcp_f32_e32 v152, v152
	v_rcp_f32_e32 v153, v153
	s_nop 0
	v_pk_mul_f32 v[146:147], v[146:147], v[148:149]
	v_pk_mul_f32 v[150:151], v[150:151], v[152:153]
	v_pk_mul_f32 v[22:23], v[22:23], v[146:147]
	v_pk_mul_f32 v[24:25], v[24:25], v[150:151]
	v_lshlrev_b32_e32 v168, 16, v202
	v_and_b32_e32 v169, 0xffff0000, v202
	v_lshlrev_b32_e32 v178, 16, v210
	v_and_b32_e32 v179, 0xffff0000, v210
	v_lshlrev_b32_e32 v180, 16, v203
	v_and_b32_e32 v181, 0xffff0000, v203
	v_lshlrev_b32_e32 v244, 16, v211
	v_and_b32_e32 v245, 0xffff0000, v211
	v_max_f32_e32 v178, s100, v178
	v_max_f32_e32 v179, s100, v179
	v_max_f32_e32 v168, s100, v168
	v_max_f32_e32 v169, s100, v169
	v_max_f32_e32 v244, s100, v244
	v_max_f32_e32 v245, s100, v245
	v_max_f32_e32 v180, s100, v180
	v_max_f32_e32 v181, s100, v181
	v_rcp_f32_e32 v178, v178
	v_rcp_f32_e32 v179, v179
	v_rcp_f32_e32 v244, v244
	v_rcp_f32_e32 v245, v245
	s_nop 0
	v_pk_mul_f32 v[168:169], v[168:169], v[178:179]
	v_pk_mul_f32 v[180:181], v[180:181], v[244:245]
	v_pk_mul_f32 v[14:15], v[14:15], v[168:169]
	v_pk_mul_f32 v[16:17], v[16:17], v[180:181]
	v_lshlrev_b32_e32 v168, 16, v204
	v_and_b32_e32 v169, 0xffff0000, v204
	v_lshlrev_b32_e32 v178, 16, v212
	v_and_b32_e32 v179, 0xffff0000, v212
	v_lshlrev_b32_e32 v180, 16, v205
	v_and_b32_e32 v181, 0xffff0000, v205
	v_lshlrev_b32_e32 v244, 16, v213
	v_and_b32_e32 v245, 0xffff0000, v213
	v_max_f32_e32 v178, s100, v178
	v_max_f32_e32 v179, s100, v179
	v_max_f32_e32 v168, s100, v168
	v_max_f32_e32 v169, s100, v169
	v_max_f32_e32 v244, s100, v244
	v_max_f32_e32 v245, s100, v245
	v_max_f32_e32 v180, s100, v180
	v_max_f32_e32 v181, s100, v181
	v_rcp_f32_e32 v178, v178
	v_rcp_f32_e32 v179, v179
	v_rcp_f32_e32 v244, v244
	v_rcp_f32_e32 v245, v245
	s_nop 0
	v_pk_mul_f32 v[168:169], v[168:169], v[178:179]
	v_pk_mul_f32 v[180:181], v[180:181], v[244:245]
	v_pk_mul_f32 v[6:7], v[6:7], v[168:169]
	v_pk_mul_f32 v[8:9], v[8:9], v[180:181]
	v_lshlrev_b32_e32 v146, 16, v206
	v_and_b32_e32 v147, 0xffff0000, v206
	v_lshlrev_b32_e32 v148, 16, v214
	v_and_b32_e32 v149, 0xffff0000, v214
	v_lshlrev_b32_e32 v150, 16, v207
	v_and_b32_e32 v151, 0xffff0000, v207
	v_lshlrev_b32_e32 v152, 16, v215
	v_and_b32_e32 v153, 0xffff0000, v215
	v_max_f32_e32 v148, s100, v148
	v_max_f32_e32 v149, s100, v149
	v_max_f32_e32 v146, s100, v146
	v_max_f32_e32 v147, s100, v147
	v_max_f32_e32 v152, s100, v152
	v_max_f32_e32 v153, s100, v153
	v_max_f32_e32 v150, s100, v150
	v_max_f32_e32 v151, s100, v151
	v_rcp_f32_e32 v148, v148
	v_rcp_f32_e32 v149, v149
	v_rcp_f32_e32 v152, v152
	v_rcp_f32_e32 v153, v153
	s_nop 0
	v_pk_mul_f32 v[146:147], v[146:147], v[148:149]
	v_pk_mul_f32 v[150:151], v[150:151], v[152:153]
	v_pk_mul_f32 v[2:3], v[2:3], v[146:147]
	v_pk_mul_f32 v[4:5], v[4:5], v[150:151]
	s_branch .Lup3_tail
; DI float bflo(unsigned w) { return __uint_as_float(w << 16); }
; DI float bfhi(unsigned w) { return __uint_as_float(w & 0xffff0000u); }
; DI u32x4 pack8(f32x4 a, f32x4 b) { u32x4 w; w.x = pk2(a[0], a[1]); w.y = pk2(a[2], a[3]); w.z = pk2(b[0], b[1]); w.w = pk2(b[2], b[3]); return w; }
;     DI void operator()(Acc& acc, const Unit& u, int wr, int wc, int fr, int fq) const {
;     ...
;                     for (int bj = 0; bj < 2; ++bj) g[ai][m][bj] = *(const u32x4*)(base + (size_t)(ai * 128 + m * 16) * NPJ + u.k * 1024 + bj * 128);
; #pragma unroll
;             for (int ai = 0; ai < 2; ++ai)
; #pragma unroll
;                 for (int m = 0; m < 4; ++m)
; #pragma unroll
;                     for (int bj = 0; bj < 2; ++bj) { const u32x4 q = g[ai][m][bj]; f32x4& v0 = acc[ai][bj][m][0]; f32x4& v1 = acc[ai][bj][m][1];
;                         v0[0] *= bflo(q.x); v0[1] *= bfhi(q.x); v0[2] *= bflo(q.y); v0[3] *= bfhi(q.y); v1[0] *= bflo(q.z); v1[1] *= bfhi(q.z); v1[2] *= bflo(q.w); v1[3] *= bfhi(q.w); }
;         }
;         if (u.k > 0) {
;             u32x4 g[2][4][2];
; #pragma unroll
;             for (int ai = 0; ai < 2; ++ai)
; #pragma unroll
;                 for (int m = 0; m < 4; ++m)
; #pragma unroll
;                     for (int bj = 0; bj < 2; ++bj) g[ai][m][bj] = *(const u32x4*)(base + (size_t)(ai * 128 + m * 16) * NPJ + bj * 128);
; #pragma unroll
;             for (int ai = 0; ai < 2; ++ai)
; #pragma unroll
;                 for (int m = 0; m < 4; ++m)
; #pragma unroll
;                     for (int bj = 0; bj < 2; ++bj) { const u32x4 q = g[ai][m][bj]; f32x4& v0 = acc[ai][bj][m][0]; f32x4& v1 = acc[ai][bj][m][1];
;                         v0[0] += bflo(q.x); v0[1] += bfhi(q.x); v0[2] += bflo(q.y); v0[3] += bfhi(q.y); v1[0] += bflo(q.z); v1[1] += bfhi(q.z); v1[2] += bflo(q.w); v1[3] += bfhi(q.w); }
;         }
;         if (!dry) {
; #pragma unroll
;             for (int ai = 0; ai < 2; ++ai)
; #pragma unroll
;                 for (int m = 0; m < 4; ++m)
; #pragma unroll
;                     for (int bj = 0; bj < 2; ++bj) *(u32x4*)(base + (size_t)(ai * 128 + m * 16) * NPJ + bj * 128) = pack8(acc[ai][bj][m][0], acc[ai][bj][m][1]);
.Lup3_final:
	global_load_dwordx4 v[184:187], v[130:131], off
	global_load_dwordx4 v[188:191], v[130:131], off offset:256
	global_load_dwordx4 v[192:195], v[132:133], off
	global_load_dwordx4 v[196:199], v[132:133], off offset:256
	global_load_dwordx4 v[200:203], v[134:135], off
	global_load_dwordx4 v[204:207], v[134:135], off offset:256
	global_load_dwordx4 v[208:211], v[136:137], off
	global_load_dwordx4 v[212:215], v[136:137], off offset:256
	global_load_dwordx4 v[216:219], v[138:139], off
	global_load_dwordx4 v[220:223], v[138:139], off offset:256
	global_load_dwordx4 v[224:227], v[140:141], off
	global_load_dwordx4 v[228:231], v[140:141], off offset:256
	s_waitcnt vmcnt(10)
	v_lshlrev_b32_e32 v146, 16, v184
	v_and_b32_e32 v147, 0xffff0000, v184
	v_lshlrev_b32_e32 v148, 16, v185
	v_and_b32_e32 v149, 0xffff0000, v185
	v_lshlrev_b32_e32 v150, 16, v186
	v_and_b32_e32 v151, 0xffff0000, v186
	v_lshlrev_b32_e32 v152, 16, v187
	v_and_b32_e32 v153, 0xffff0000, v187
	v_max_f32_e32 v146, s100, v146
	v_max_f32_e32 v147, s100, v147
	v_max_f32_e32 v148, s100, v148
	v_max_f32_e32 v149, s100, v149
	v_max_f32_e32 v150, s100, v150
	v_max_f32_e32 v151, s100, v151
	v_max_f32_e32 v152, s100, v152
	v_max_f32_e32 v153, s100, v153
	v_pk_mul_f32 v[126:127], v[126:127], v[146:147]
	v_pk_mul_f32 v[128:129], v[128:129], v[148:149]
	v_pk_mul_f32 v[122:123], v[122:123], v[150:151]
	v_pk_mul_f32 v[124:125], v[124:125], v[152:153]
	v_cvt_pk_bf16_f32 v184, v126, v127
	v_cvt_pk_bf16_f32 v185, v128, v129
	v_cvt_pk_bf16_f32 v186, v122, v123
	v_cvt_pk_bf16_f32 v187, v124, v125
	v_lshlrev_b32_e32 v168, 16, v188
	v_and_b32_e32 v169, 0xffff0000, v188
	v_lshlrev_b32_e32 v178, 16, v189
	v_and_b32_e32 v179, 0xffff0000, v189
	v_lshlrev_b32_e32 v180, 16, v190
	v_and_b32_e32 v181, 0xffff0000, v190
	v_lshlrev_b32_e32 v244, 16, v191
	v_and_b32_e32 v245, 0xffff0000, v191
	v_max_f32_e32 v168, s100, v168
	v_max_f32_e32 v169, s100, v169
	v_max_f32_e32 v178, s100, v178
	v_max_f32_e32 v179, s100, v179
	v_max_f32_e32 v180, s100, v180
	v_max_f32_e32 v181, s100, v181
	v_max_f32_e32 v244, s100, v244
	v_max_f32_e32 v245, s100, v245
	v_pk_mul_f32 v[114:115], v[114:115], v[168:169]
	v_pk_mul_f32 v[116:117], v[116:117], v[178:179]
	v_pk_mul_f32 v[110:111], v[110:111], v[180:181]
	v_pk_mul_f32 v[112:113], v[112:113], v[244:245]
	v_cvt_pk_bf16_f32 v188, v114, v115
	v_cvt_pk_bf16_f32 v189, v116, v117
	v_cvt_pk_bf16_f32 v190, v110, v111
	v_cvt_pk_bf16_f32 v191, v112, v113
	global_store_dwordx4 v[130:131], v[184:187], off offset:-4096
	global_store_dwordx4 v[130:131], v[188:191], off offset:-3840
	s_nop 1
	global_load_dwordx4 v[184:187], v[142:143], off
	global_load_dwordx4 v[188:191], v[142:143], off offset:256
	s_waitcnt vmcnt(12)
	v_lshlrev_b32_e32 v146, 16, v192
	v_and_b32_e32 v147, 0xffff0000, v192
	v_lshlrev_b32_e32 v148, 16, v193
	v_and_b32_e32 v149, 0xffff0000, v193
	v_lshlrev_b32_e32 v150, 16, v194
	v_and_b32_e32 v151, 0xffff0000, v194
	v_lshlrev_b32_e32 v152, 16, v195
	v_and_b32_e32 v153, 0xffff0000, v195
	v_max_f32_e32 v146, s100, v146
	v_max_f32_e32 v147, s100, v147
	v_max_f32_e32 v148, s100, v148
	v_max_f32_e32 v149, s100, v149
	v_max_f32_e32 v150, s100, v150
	v_max_f32_e32 v151, s100, v151
	v_max_f32_e32 v152, s100, v152
	v_max_f32_e32 v153, s100, v153
	v_pk_mul_f32 v[118:119], v[118:119], v[146:147]
	v_pk_mul_f32 v[120:121], v[120:121], v[148:149]
	v_pk_mul_f32 v[106:107], v[106:107], v[150:151]
	v_pk_mul_f32 v[108:109], v[108:109], v[152:153]
	v_cvt_pk_bf16_f32 v192, v118, v119
	v_cvt_pk_bf16_f32 v193, v120, v121
	v_cvt_pk_bf16_f32 v194, v106, v107
	v_cvt_pk_bf16_f32 v195, v108, v109
	v_lshlrev_b32_e32 v168, 16, v196
	v_and_b32_e32 v169, 0xffff0000, v196
	v_lshlrev_b32_e32 v178, 16, v197
	v_and_b32_e32 v179, 0xffff0000, v197
	v_lshlrev_b32_e32 v180, 16, v198
	v_and_b32_e32 v181, 0xffff0000, v198
	v_lshlrev_b32_e32 v244, 16, v199
	v_and_b32_e32 v245, 0xffff0000, v199
	v_max_f32_e32 v168, s100, v168
	v_max_f32_e32 v169, s100, v169
	v_max_f32_e32 v178, s100, v178
	v_max_f32_e32 v179, s100, v179
	v_max_f32_e32 v180, s100, v180
	v_max_f32_e32 v181, s100, v181
	v_max_f32_e32 v244, s100, v244
	v_max_f32_e32 v245, s100, v245
	v_pk_mul_f32 v[98:99], v[98:99], v[168:169]
	v_pk_mul_f32 v[100:101], v[100:101], v[178:179]
	v_pk_mul_f32 v[90:91], v[90:91], v[180:181]
	v_pk_mul_f32 v[92:93], v[92:93], v[244:245]
	v_cvt_pk_bf16_f32 v196, v98, v99
	v_cvt_pk_bf16_f32 v197, v100, v101
	v_cvt_pk_bf16_f32 v198, v90, v91
	v_cvt_pk_bf16_f32 v199, v92, v93
	global_store_dwordx4 v[132:133], v[192:195], off offset:-4096
	global_store_dwordx4 v[132:133], v[196:199], off offset:-3840
	s_nop 1
	global_load_dwordx4 v[192:195], v[144:145], off
	global_load_dwordx4 v[196:199], v[144:145], off offset:256
	s_waitcnt vmcnt(14)
; DI float bflo(unsigned w) { return __uint_as_float(w << 16); }
; DI float bfhi(unsigned w) { return __uint_as_float(w & 0xffff0000u); }
; DI u32x4 pack8(f32x4 a, f32x4 b) { u32x4 w; w.x = pk2(a[0], a[1]); w.y = pk2(a[2], a[3]); w.z = pk2(b[0], b[1]); w.w = pk2(b[2], b[3]); return w; }
;     DI void operator()(Acc& acc, const Unit& u, int wr, int wc, int fr, int fq) const {
;     ...
;                     for (int bj = 0; bj < 2; ++bj) g[ai][m][bj] = *(const u32x4*)(base + (size_t)(ai * 128 + m * 16) * NPJ + u.k * 1024 + bj * 128);
; #pragma unroll
;             for (int ai = 0; ai < 2; ++ai)
; #pragma unroll
;                 for (int m = 0; m < 4; ++m)
; #pragma unroll
;                     for (int bj = 0; bj < 2; ++bj) { const u32x4 q = g[ai][m][bj]; f32x4& v0 = acc[ai][bj][m][0]; f32x4& v1 = acc[ai][bj][m][1];
;                         v0[0] *= bflo(q.x); v0[1] *= bfhi(q.x); v0[2] *= bflo(q.y); v0[3] *= bfhi(q.y); v1[0] *= bflo(q.z); v1[1] *= bfhi(q.z); v1[2] *= bflo(q.w); v1[3] *= bfhi(q.w); }
;         }
;         if (u.k > 0) {
;             u32x4 g[2][4][2];
; #pragma unroll
;             for (int ai = 0; ai < 2; ++ai)
; #pragma unroll
;                 for (int m = 0; m < 4; ++m)
; #pragma unroll
;                     for (int bj = 0; bj < 2; ++bj) g[ai][m][bj] = *(const u32x4*)(base + (size_t)(ai * 128 + m * 16) * NPJ + bj * 128);
; #pragma unroll
;             for (int ai = 0; ai < 2; ++ai)
; #pragma unroll
;                 for (int m = 0; m < 4; ++m)
; #pragma unroll
;                     for (int bj = 0; bj < 2; ++bj) { const u32x4 q = g[ai][m][bj]; f32x4& v0 = acc[ai][bj][m][0]; f32x4& v1 = acc[ai][bj][m][1];
;                         v0[0] += bflo(q.x); v0[1] += bfhi(q.x); v0[2] += bflo(q.y); v0[3] += bfhi(q.y); v1[0] += bflo(q.z); v1[1] += bfhi(q.z); v1[2] += bflo(q.w); v1[3] += bfhi(q.w); }
;         }
;         if (!dry) {
; #pragma unroll
;             for (int ai = 0; ai < 2; ++ai)
; #pragma unroll
;                 for (int m = 0; m < 4; ++m)
; #pragma unroll
;                     for (int bj = 0; bj < 2; ++bj) *(u32x4*)(base + (size_t)(ai * 128 + m * 16) * NPJ + bj * 128) = pack8(acc[ai][bj][m][0], acc[ai][bj][m][1]);
	v_lshlrev_b32_e32 v146, 16, v200
	v_and_b32_e32 v147, 0xffff0000, v200
	v_lshlrev_b32_e32 v148, 16, v201
	v_and_b32_e32 v149, 0xffff0000, v201
	v_lshlrev_b32_e32 v150, 16, v202
	v_and_b32_e32 v151, 0xffff0000, v202
	v_lshlrev_b32_e32 v152, 16, v203
	v_and_b32_e32 v153, 0xffff0000, v203
	v_max_f32_e32 v146, s100, v146
	v_max_f32_e32 v147, s100, v147
	v_max_f32_e32 v148, s100, v148
	v_max_f32_e32 v149, s100, v149
	v_max_f32_e32 v150, s100, v150
	v_max_f32_e32 v151, s100, v151
	v_max_f32_e32 v152, s100, v152
	v_max_f32_e32 v153, s100, v153
	v_pk_mul_f32 v[102:103], v[102:103], v[146:147]
	v_pk_mul_f32 v[104:105], v[104:105], v[148:149]
	v_pk_mul_f32 v[94:95], v[94:95], v[150:151]
	v_pk_mul_f32 v[96:97], v[96:97], v[152:153]
	v_cvt_pk_bf16_f32 v200, v102, v103
	v_cvt_pk_bf16_f32 v201, v104, v105
	v_cvt_pk_bf16_f32 v202, v94, v95
	v_cvt_pk_bf16_f32 v203, v96, v97
	v_lshlrev_b32_e32 v168, 16, v204
	v_and_b32_e32 v169, 0xffff0000, v204
	v_lshlrev_b32_e32 v178, 16, v205
	v_and_b32_e32 v179, 0xffff0000, v205
	v_lshlrev_b32_e32 v180, 16, v206
	v_and_b32_e32 v181, 0xffff0000, v206
	v_lshlrev_b32_e32 v244, 16, v207
	v_and_b32_e32 v245, 0xffff0000, v207
	v_max_f32_e32 v168, s100, v168
	v_max_f32_e32 v169, s100, v169
	v_max_f32_e32 v178, s100, v178
	v_max_f32_e32 v179, s100, v179
	v_max_f32_e32 v180, s100, v180
	v_max_f32_e32 v181, s100, v181
	v_max_f32_e32 v244, s100, v244
	v_max_f32_e32 v245, s100, v245
	v_pk_mul_f32 v[82:83], v[82:83], v[168:169]
	v_pk_mul_f32 v[84:85], v[84:85], v[178:179]
	v_pk_mul_f32 v[74:75], v[74:75], v[180:181]
	v_pk_mul_f32 v[76:77], v[76:77], v[244:245]
	v_cvt_pk_bf16_f32 v204, v82, v83
	v_cvt_pk_bf16_f32 v205, v84, v85
	v_cvt_pk_bf16_f32 v206, v74, v75
	v_cvt_pk_bf16_f32 v207, v76, v77
	global_store_dwordx4 v[134:135], v[200:203], off offset:-4096
	global_store_dwordx4 v[134:135], v[204:207], off offset:-3840
	s_waitcnt vmcnt(14)
	v_lshlrev_b32_e32 v146, 16, v208
	v_and_b32_e32 v147, 0xffff0000, v208
	v_lshlrev_b32_e32 v148, 16, v209
	v_and_b32_e32 v149, 0xffff0000, v209
	v_lshlrev_b32_e32 v150, 16, v210
	v_and_b32_e32 v151, 0xffff0000, v210
	v_lshlrev_b32_e32 v152, 16, v211
	v_and_b32_e32 v153, 0xffff0000, v211
	v_max_f32_e32 v146, s100, v146
	v_max_f32_e32 v147, s100, v147
	v_max_f32_e32 v148, s100, v148
	v_max_f32_e32 v149, s100, v149
	v_max_f32_e32 v150, s100, v150
	v_max_f32_e32 v151, s100, v151
	v_max_f32_e32 v152, s100, v152
	v_max_f32_e32 v153, s100, v153
	v_pk_mul_f32 v[86:87], v[86:87], v[146:147]
	v_pk_mul_f32 v[88:89], v[88:89], v[148:149]
	v_pk_mul_f32 v[78:79], v[78:79], v[150:151]
	v_pk_mul_f32 v[80:81], v[80:81], v[152:153]
	v_cvt_pk_bf16_f32 v208, v86, v87
	v_cvt_pk_bf16_f32 v209, v88, v89
	v_cvt_pk_bf16_f32 v210, v78, v79
	v_cvt_pk_bf16_f32 v211, v80, v81
	v_lshlrev_b32_e32 v168, 16, v212
	v_and_b32_e32 v169, 0xffff0000, v212
	v_lshlrev_b32_e32 v178, 16, v213
	v_and_b32_e32 v179, 0xffff0000, v213
	v_lshlrev_b32_e32 v180, 16, v214
	v_and_b32_e32 v181, 0xffff0000, v214
	v_lshlrev_b32_e32 v244, 16, v215
	v_and_b32_e32 v245, 0xffff0000, v215
	v_max_f32_e32 v168, s100, v168
	v_max_f32_e32 v169, s100, v169
	v_max_f32_e32 v178, s100, v178
	v_max_f32_e32 v179, s100, v179
	v_max_f32_e32 v180, s100, v180
	v_max_f32_e32 v181, s100, v181
	v_max_f32_e32 v244, s100, v244
	v_max_f32_e32 v245, s100, v245
	v_pk_mul_f32 v[70:71], v[70:71], v[168:169]
	v_pk_mul_f32 v[72:73], v[72:73], v[178:179]
	v_pk_mul_f32 v[66:67], v[66:67], v[180:181]
	v_pk_mul_f32 v[68:69], v[68:69], v[244:245]
	v_cvt_pk_bf16_f32 v212, v70, v71
	v_cvt_pk_bf16_f32 v213, v72, v73
	v_cvt_pk_bf16_f32 v214, v66, v67
	v_cvt_pk_bf16_f32 v215, v68, v69
	global_store_dwordx4 v[136:137], v[208:211], off offset:-4096
	global_store_dwordx4 v[136:137], v[212:215], off offset:-3840
	s_waitcnt vmcnt(14)
	v_lshlrev_b32_e32 v146, 16, v216
	v_and_b32_e32 v147, 0xffff0000, v216
	v_lshlrev_b32_e32 v148, 16, v217
	v_and_b32_e32 v149, 0xffff0000, v217
	v_lshlrev_b32_e32 v150, 16, v218
	v_and_b32_e32 v151, 0xffff0000, v218
	v_lshlrev_b32_e32 v152, 16, v219
	v_and_b32_e32 v153, 0xffff0000, v219
	v_max_f32_e32 v146, s100, v146
	v_max_f32_e32 v147, s100, v147
	v_max_f32_e32 v148, s100, v148
	v_max_f32_e32 v149, s100, v149
	v_max_f32_e32 v150, s100, v150
	v_max_f32_e32 v151, s100, v151
	v_max_f32_e32 v152, s100, v152
	v_max_f32_e32 v153, s100, v153
	v_pk_mul_f32 v[62:63], v[62:63], v[146:147]
	v_pk_mul_f32 v[64:65], v[64:65], v[148:149]
	v_pk_mul_f32 v[58:59], v[58:59], v[150:151]
	v_pk_mul_f32 v[60:61], v[60:61], v[152:153]
	v_cvt_pk_bf16_f32 v216, v62, v63
	v_cvt_pk_bf16_f32 v217, v64, v65
	v_cvt_pk_bf16_f32 v218, v58, v59
	v_cvt_pk_bf16_f32 v219, v60, v61
	v_lshlrev_b32_e32 v168, 16, v220
	v_and_b32_e32 v169, 0xffff0000, v220
	v_lshlrev_b32_e32 v178, 16, v221
	v_and_b32_e32 v179, 0xffff0000, v221
	v_lshlrev_b32_e32 v180, 16, v222
	v_and_b32_e32 v181, 0xffff0000, v222
	v_lshlrev_b32_e32 v244, 16, v223
	v_and_b32_e32 v245, 0xffff0000, v223
	v_max_f32_e32 v168, s100, v168
	v_max_f32_e32 v169, s100, v169
	v_max_f32_e32 v178, s100, v178
	v_max_f32_e32 v179, s100, v179
	v_max_f32_e32 v180, s100, v180
	v_max_f32_e32 v181, s100, v181
	v_max_f32_e32 v244, s100, v244
	v_max_f32_e32 v245, s100, v245
	v_pk_mul_f32 v[50:51], v[50:51], v[168:169]
	v_pk_mul_f32 v[52:53], v[52:53], v[178:179]
	v_pk_mul_f32 v[42:43], v[42:43], v[180:181]
	v_pk_mul_f32 v[44:45], v[44:45], v[244:245]
	v_cvt_pk_bf16_f32 v220, v50, v51
	v_cvt_pk_bf16_f32 v221, v52, v53
	v_cvt_pk_bf16_f32 v222, v42, v43
	v_cvt_pk_bf16_f32 v223, v44, v45
	global_store_dwordx4 v[138:139], v[216:219], off offset:-4096
	global_store_dwordx4 v[138:139], v[220:223], off offset:-3840
	s_waitcnt vmcnt(14)
; DI float bflo(unsigned w) { return __uint_as_float(w << 16); }
; DI float bfhi(unsigned w) { return __uint_as_float(w & 0xffff0000u); }
; DI u32x4 pack8(f32x4 a, f32x4 b) { u32x4 w; w.x = pk2(a[0], a[1]); w.y = pk2(a[2], a[3]); w.z = pk2(b[0], b[1]); w.w = pk2(b[2], b[3]); return w; }
;     DI void operator()(Acc& acc, const Unit& u, int wr, int wc, int fr, int fq) const {
;     ...
;                     for (int bj = 0; bj < 2; ++bj) g[ai][m][bj] = *(const u32x4*)(base + (size_t)(ai * 128 + m * 16) * NPJ + u.k * 1024 + bj * 128);
; #pragma unroll
;             for (int ai = 0; ai < 2; ++ai)
; #pragma unroll
;                 for (int m = 0; m < 4; ++m)
; #pragma unroll
;                     for (int bj = 0; bj < 2; ++bj) { const u32x4 q = g[ai][m][bj]; f32x4& v0 = acc[ai][bj][m][0]; f32x4& v1 = acc[ai][bj][m][1];
;                         v0[0] *= bflo(q.x); v0[1] *= bfhi(q.x); v0[2] *= bflo(q.y); v0[3] *= bfhi(q.y); v1[0] *= bflo(q.z); v1[1] *= bfhi(q.z); v1[2] *= bflo(q.w); v1[3] *= bfhi(q.w); }
;         }
;         if (u.k > 0) {
;             u32x4 g[2][4][2];
; #pragma unroll
;             for (int ai = 0; ai < 2; ++ai)
; #pragma unroll
;                 for (int m = 0; m < 4; ++m)
; #pragma unroll
;                     for (int bj = 0; bj < 2; ++bj) g[ai][m][bj] = *(const u32x4*)(base + (size_t)(ai * 128 + m * 16) * NPJ + bj * 128);
; #pragma unroll
;             for (int ai = 0; ai < 2; ++ai)
; #pragma unroll
;                 for (int m = 0; m < 4; ++m)
; #pragma unroll
;                     for (int bj = 0; bj < 2; ++bj) { const u32x4 q = g[ai][m][bj]; f32x4& v0 = acc[ai][bj][m][0]; f32x4& v1 = acc[ai][bj][m][1];
;                         v0[0] += bflo(q.x); v0[1] += bfhi(q.x); v0[2] += bflo(q.y); v0[3] += bfhi(q.y); v1[0] += bflo(q.z); v1[1] += bfhi(q.z); v1[2] += bflo(q.w); v1[3] += bfhi(q.w); }
;         }
;         if (!dry) {
; #pragma unroll
;             for (int ai = 0; ai < 2; ++ai)
; #pragma unroll
;                 for (int m = 0; m < 4; ++m)
; #pragma unroll
;                     for (int bj = 0; bj < 2; ++bj) *(u32x4*)(base + (size_t)(ai * 128 + m * 16) * NPJ + bj * 128) = pack8(acc[ai][bj][m][0], acc[ai][bj][m][1]);
	v_lshlrev_b32_e32 v146, 16, v224
	v_and_b32_e32 v147, 0xffff0000, v224
	v_lshlrev_b32_e32 v148, 16, v225
	v_and_b32_e32 v149, 0xffff0000, v225
	v_lshlrev_b32_e32 v150, 16, v226
	v_and_b32_e32 v151, 0xffff0000, v226
	v_lshlrev_b32_e32 v152, 16, v227
	v_and_b32_e32 v153, 0xffff0000, v227
	v_max_f32_e32 v146, s100, v146
	v_max_f32_e32 v147, s100, v147
	v_max_f32_e32 v148, s100, v148
	v_max_f32_e32 v149, s100, v149
	v_max_f32_e32 v150, s100, v150
	v_max_f32_e32 v151, s100, v151
	v_max_f32_e32 v152, s100, v152
	v_max_f32_e32 v153, s100, v153
	v_pk_mul_f32 v[54:55], v[54:55], v[146:147]
	v_pk_mul_f32 v[56:57], v[56:57], v[148:149]
	v_pk_mul_f32 v[46:47], v[46:47], v[150:151]
	v_pk_mul_f32 v[48:49], v[48:49], v[152:153]
	v_cvt_pk_bf16_f32 v224, v54, v55
	v_cvt_pk_bf16_f32 v225, v56, v57
	v_cvt_pk_bf16_f32 v226, v46, v47
	v_cvt_pk_bf16_f32 v227, v48, v49
	v_lshlrev_b32_e32 v168, 16, v228
	v_and_b32_e32 v169, 0xffff0000, v228
	v_lshlrev_b32_e32 v178, 16, v229
	v_and_b32_e32 v179, 0xffff0000, v229
	v_lshlrev_b32_e32 v180, 16, v230
	v_and_b32_e32 v181, 0xffff0000, v230
	v_lshlrev_b32_e32 v244, 16, v231
	v_and_b32_e32 v245, 0xffff0000, v231
	v_max_f32_e32 v168, s100, v168
	v_max_f32_e32 v169, s100, v169
	v_max_f32_e32 v178, s100, v178
	v_max_f32_e32 v179, s100, v179
	v_max_f32_e32 v180, s100, v180
	v_max_f32_e32 v181, s100, v181
	v_max_f32_e32 v244, s100, v244
	v_max_f32_e32 v245, s100, v245
	v_pk_mul_f32 v[34:35], v[34:35], v[168:169]
	v_pk_mul_f32 v[36:37], v[36:37], v[178:179]
	v_pk_mul_f32 v[26:27], v[26:27], v[180:181]
	v_pk_mul_f32 v[28:29], v[28:29], v[244:245]
	v_cvt_pk_bf16_f32 v228, v34, v35
	v_cvt_pk_bf16_f32 v229, v36, v37
	v_cvt_pk_bf16_f32 v230, v26, v27
	v_cvt_pk_bf16_f32 v231, v28, v29
	global_store_dwordx4 v[140:141], v[224:227], off offset:-4096
	global_store_dwordx4 v[140:141], v[228:231], off offset:-3840
	s_waitcnt vmcnt(12)
	v_lshlrev_b32_e32 v146, 16, v184
	v_and_b32_e32 v147, 0xffff0000, v184
	v_lshlrev_b32_e32 v148, 16, v185
	v_and_b32_e32 v149, 0xffff0000, v185
	v_lshlrev_b32_e32 v150, 16, v186
	v_and_b32_e32 v151, 0xffff0000, v186
	v_lshlrev_b32_e32 v152, 16, v187
	v_and_b32_e32 v153, 0xffff0000, v187
	v_max_f32_e32 v146, s100, v146
	v_max_f32_e32 v147, s100, v147
	v_max_f32_e32 v148, s100, v148
	v_max_f32_e32 v149, s100, v149
	v_max_f32_e32 v150, s100, v150
	v_max_f32_e32 v151, s100, v151
	v_max_f32_e32 v152, s100, v152
	v_max_f32_e32 v153, s100, v153
	v_pk_mul_f32 v[38:39], v[38:39], v[146:147]
	v_pk_mul_f32 v[40:41], v[40:41], v[148:149]
	v_pk_mul_f32 v[30:31], v[30:31], v[150:151]
	v_pk_mul_f32 v[32:33], v[32:33], v[152:153]
	v_cvt_pk_bf16_f32 v184, v38, v39
	v_cvt_pk_bf16_f32 v185, v40, v41
	v_cvt_pk_bf16_f32 v186, v30, v31
	v_cvt_pk_bf16_f32 v187, v32, v33
	v_lshlrev_b32_e32 v168, 16, v188
	v_and_b32_e32 v169, 0xffff0000, v188
	v_lshlrev_b32_e32 v178, 16, v189
	v_and_b32_e32 v179, 0xffff0000, v189
	v_lshlrev_b32_e32 v180, 16, v190
	v_and_b32_e32 v181, 0xffff0000, v190
	v_lshlrev_b32_e32 v244, 16, v191
	v_and_b32_e32 v245, 0xffff0000, v191
	v_max_f32_e32 v168, s100, v168
	v_max_f32_e32 v169, s100, v169
	v_max_f32_e32 v178, s100, v178
	v_max_f32_e32 v179, s100, v179
	v_max_f32_e32 v180, s100, v180
	v_max_f32_e32 v181, s100, v181
	v_max_f32_e32 v244, s100, v244
	v_max_f32_e32 v245, s100, v245
	v_pk_mul_f32 v[18:19], v[18:19], v[168:169]
	v_pk_mul_f32 v[20:21], v[20:21], v[178:179]
	v_pk_mul_f32 v[10:11], v[10:11], v[180:181]
	v_pk_mul_f32 v[12:13], v[12:13], v[244:245]
	v_cvt_pk_bf16_f32 v188, v18, v19
	v_cvt_pk_bf16_f32 v189, v20, v21
	v_cvt_pk_bf16_f32 v190, v10, v11
	v_cvt_pk_bf16_f32 v191, v12, v13
	global_store_dwordx4 v[142:143], v[184:187], off offset:-4096
	global_store_dwordx4 v[142:143], v[188:191], off offset:-3840
	s_waitcnt vmcnt(10)
	v_lshlrev_b32_e32 v146, 16, v192
	v_and_b32_e32 v147, 0xffff0000, v192
	v_lshlrev_b32_e32 v148, 16, v193
	v_and_b32_e32 v149, 0xffff0000, v193
	v_lshlrev_b32_e32 v150, 16, v194
	v_and_b32_e32 v151, 0xffff0000, v194
	v_lshlrev_b32_e32 v152, 16, v195
	v_and_b32_e32 v153, 0xffff0000, v195
	v_max_f32_e32 v146, s100, v146
	v_max_f32_e32 v147, s100, v147
	v_max_f32_e32 v148, s100, v148
	v_max_f32_e32 v149, s100, v149
	v_max_f32_e32 v150, s100, v150
	v_max_f32_e32 v151, s100, v151
	v_max_f32_e32 v152, s100, v152
	v_max_f32_e32 v153, s100, v153
	v_pk_mul_f32 v[22:23], v[22:23], v[146:147]
	v_pk_mul_f32 v[24:25], v[24:25], v[148:149]
	v_pk_mul_f32 v[14:15], v[14:15], v[150:151]
	v_pk_mul_f32 v[16:17], v[16:17], v[152:153]
	v_cvt_pk_bf16_f32 v192, v22, v23
	v_cvt_pk_bf16_f32 v193, v24, v25
	v_cvt_pk_bf16_f32 v194, v14, v15
	v_cvt_pk_bf16_f32 v195, v16, v17
	v_lshlrev_b32_e32 v168, 16, v196
	v_and_b32_e32 v169, 0xffff0000, v196
	v_lshlrev_b32_e32 v178, 16, v197
	v_and_b32_e32 v179, 0xffff0000, v197
	v_lshlrev_b32_e32 v180, 16, v198
	v_and_b32_e32 v181, 0xffff0000, v198
	v_lshlrev_b32_e32 v244, 16, v199
	v_and_b32_e32 v245, 0xffff0000, v199
	v_max_f32_e32 v168, s100, v168
	v_max_f32_e32 v169, s100, v169
	v_max_f32_e32 v178, s100, v178
	v_max_f32_e32 v179, s100, v179
	v_max_f32_e32 v180, s100, v180
	v_max_f32_e32 v181, s100, v181
	v_max_f32_e32 v244, s100, v244
	v_max_f32_e32 v245, s100, v245
	v_pk_mul_f32 v[6:7], v[6:7], v[168:169]
	v_pk_mul_f32 v[8:9], v[8:9], v[178:179]
	v_pk_mul_f32 v[2:3], v[2:3], v[180:181]
	v_pk_mul_f32 v[4:5], v[4:5], v[244:245]
	v_cvt_pk_bf16_f32 v196, v6, v7
	v_cvt_pk_bf16_f32 v197, v8, v9
	v_cvt_pk_bf16_f32 v198, v2, v3
	v_cvt_pk_bf16_f32 v199, v4, v5
	global_store_dwordx4 v[144:145], v[192:195], off offset:-4096
	global_store_dwordx4 v[144:145], v[196:199], off offset:-3840
.Lup3_tail:
	s_cmp_eq_u32 s84, 2
	s_mov_b64 s[22:23], -1
	s_cbranch_scc1 .LBB0_943
	s_andn2_b64 vcc, exec, s[10:11]
	s_cbranch_vccnz .LBB0_942
	s_barrier
	s_branch .LBB0_942
